# back-edge rotation on the five GEMM K-loops: loop-carried SALU block moved in front of the loop-back barrier (barrier becomes loop head)
# speedup vs baseline: 1.0009x; 1.0009x over previous
;     ...
;     const bool has_next = unit(ui + 1, npm, npn, nkq);
;     const char* nA = has_next ? (const char*)A + (size_t)npm * tstep + (nkq > 0 ? (size_t)nkq * (K / 4) * 2 : 0) : cA;
;     const char* nB = has_next ? (const char*)Bt + (size_t)npn * tstep + (nkq > 0 ? (size_t)nkq * (K / 4) * 2 : 0) : cB;
;     const int ntu = (SPLIT && kq >= 0) ? nt / 4 : nt;
;     for (int t = 0; t < ntu; t += 2) {
;       const bool last = (t == ntu - 2);
;       const char* a1 = cA + (size_t)(t + 1) * kstep;
;       const char* a2 = last ? nA : cA + (size_t)(t + 2) * kstep;
;       const char* b2 = last ? nB : cB + (size_t)(t + 2) * kstep;
;     ...
;     for (int a = 0; a < 2; ++a)
; #pragma unroll
;       for (int b = 0; b < 2; ++b)
; #pragma unroll
;         for (int m = 0; m < 4; ++m)
; #pragma unroll
;           for (int n = 0; n < 2; ++n) acc[a][b][m][n] = (f32x4){0.f, 0.f, 0.f, 0.f};
;     pm = npm; pn = npn; kq = nkq; cA = nA; cB = nB; ++ui;
.LBB0_151:
	s_nop 0
	v_readlane_b32 s26, v254, 34
	v_readlane_b32 s27, v254, 35
	v_readlane_b32 s60, v254, 45
	s_lshl_b64 s[4:5], s[26:27], 19
	v_readlane_b32 s74, v254, 59
	v_readlane_b32 s75, v254, 60
	s_add_u32 s50, s74, s4
	s_addc_u32 s51, s75, s5
	s_and_b64 s[4:5], s[36:37], exec
	s_mov_b32 s49, s27
	s_cselect_b32 s22, s51, s1
	s_cselect_b32 s25, s50, s0
	s_lshl_b64 s[4:5], s[48:49], 19
	s_add_u32 s52, s6, s4
	s_addc_u32 s53, s7, s5
	s_and_b64 s[4:5], s[36:37], exec
	s_cselect_b32 s26, s53, s3
	s_cselect_b32 s27, s52, s2
	s_add_u32 s0, s0, 0x40080
	s_addc_u32 s1, s1, 0
	s_add_u32 s28, s2, 0x100
	v_mov_b32_e32 v2, 0
	s_addc_u32 s29, s3, 0
	s_mov_b32 s30, -2
	v_mov_b32_e32 v3, v2
	v_mov_b32_e32 v4, v2
	v_mov_b32_e32 v5, v2
	v_mov_b32_e32 v6, v2
	v_mov_b32_e32 v7, v2
	v_mov_b32_e32 v8, v2
	v_mov_b32_e32 v9, v2
	v_mov_b32_e32 v18, v2
	v_mov_b32_e32 v19, v2
	v_mov_b32_e32 v20, v2
	v_mov_b32_e32 v21, v2
	v_mov_b32_e32 v22, v2
	v_mov_b32_e32 v23, v2
	v_mov_b32_e32 v24, v2
	v_mov_b32_e32 v25, v2
	v_mov_b32_e32 v34, v2
	v_mov_b32_e32 v35, v2
	v_mov_b32_e32 v36, v2
	v_mov_b32_e32 v37, v2
	v_mov_b32_e32 v38, v2
	v_mov_b32_e32 v39, v2
	v_mov_b32_e32 v40, v2
	v_mov_b32_e32 v41, v2
	v_mov_b32_e32 v50, v2
	v_mov_b32_e32 v51, v2
	v_mov_b32_e32 v52, v2
	v_mov_b32_e32 v53, v2
	v_mov_b32_e32 v54, v2
	v_mov_b32_e32 v55, v2
	v_mov_b32_e32 v56, v2
	v_mov_b32_e32 v57, v2
	v_mov_b32_e32 v10, v2
	v_mov_b32_e32 v11, v2
	v_mov_b32_e32 v12, v2
	v_mov_b32_e32 v13, v2
	v_mov_b32_e32 v14, v2
	v_mov_b32_e32 v15, v2
	v_mov_b32_e32 v16, v2
	v_mov_b32_e32 v17, v2
	v_mov_b32_e32 v26, v2
	v_mov_b32_e32 v27, v2
	v_mov_b32_e32 v28, v2
	v_mov_b32_e32 v29, v2
	v_mov_b32_e32 v30, v2
	v_mov_b32_e32 v31, v2
	v_mov_b32_e32 v32, v2
	v_mov_b32_e32 v33, v2
	v_mov_b32_e32 v42, v2
	v_mov_b32_e32 v43, v2
	v_mov_b32_e32 v44, v2
	v_mov_b32_e32 v45, v2
	v_mov_b32_e32 v46, v2
	v_mov_b32_e32 v47, v2
	v_mov_b32_e32 v48, v2
	v_mov_b32_e32 v49, v2
	v_mov_b32_e32 v58, v2
	v_mov_b32_e32 v59, v2
	v_mov_b32_e32 v60, v2
	v_mov_b32_e32 v61, v2
	v_mov_b32_e32 v62, v2
	v_mov_b32_e32 v63, v2
	v_mov_b32_e32 v64, v2
	v_mov_b32_e32 v65, v2
	v_mov_b32_e32 v66, v2
	v_mov_b32_e32 v67, v2
	v_mov_b32_e32 v68, v2
	v_mov_b32_e32 v69, v2
	v_mov_b32_e32 v70, v2
	v_mov_b32_e32 v71, v2
	v_mov_b32_e32 v72, v2
	v_mov_b32_e32 v73, v2
	v_mov_b32_e32 v82, v2
	v_mov_b32_e32 v83, v2
	v_mov_b32_e32 v84, v2
	v_mov_b32_e32 v85, v2
	v_mov_b32_e32 v86, v2
	v_mov_b32_e32 v87, v2
	v_mov_b32_e32 v88, v2
	v_mov_b32_e32 v89, v2
	v_mov_b32_e32 v98, v2
	v_mov_b32_e32 v99, v2
	v_mov_b32_e32 v100, v2
	v_mov_b32_e32 v101, v2
	v_mov_b32_e32 v102, v2
	s_waitcnt vmcnt(0)
	v_mov_b32_e32 v103, v2
	v_mov_b32_e32 v104, v2
	v_mov_b32_e32 v105, v2
	v_mov_b32_e32 v114, v2
	v_mov_b32_e32 v115, v2
	v_mov_b32_e32 v116, v2
	v_mov_b32_e32 v117, v2
	v_mov_b32_e32 v118, v2
	v_mov_b32_e32 v119, v2
	v_mov_b32_e32 v120, v2
	v_mov_b32_e32 v121, v2
	v_mov_b32_e32 v74, v2
	v_mov_b32_e32 v75, v2
	v_mov_b32_e32 v76, v2
	v_mov_b32_e32 v77, v2
	v_mov_b32_e32 v78, v2
	v_mov_b32_e32 v79, v2
	v_mov_b32_e32 v80, v2
	v_mov_b32_e32 v81, v2
	v_mov_b32_e32 v90, v2
	v_mov_b32_e32 v91, v2
	v_mov_b32_e32 v92, v2
	v_mov_b32_e32 v93, v2
	v_mov_b32_e32 v94, v2
	v_mov_b32_e32 v95, v2
	v_mov_b32_e32 v96, v2
	v_mov_b32_e32 v97, v2
	v_mov_b32_e32 v106, v2
	v_mov_b32_e32 v107, v2
	v_mov_b32_e32 v108, v2
	v_mov_b32_e32 v109, v2
	v_mov_b32_e32 v110, v2
	v_mov_b32_e32 v111, v2
	v_mov_b32_e32 v112, v2
	v_mov_b32_e32 v113, v2
	v_mov_b32_e32 v122, v2
	v_mov_b32_e32 v123, v2
	v_mov_b32_e32 v124, v2
	v_mov_b32_e32 v125, v2
	v_mov_b32_e32 v126, v2
	v_mov_b32_e32 v127, v2
	v_mov_b32_e32 v128, v2
	v_mov_b32_e32 v129, v2
	v_readlane_b32 s61, v254, 46
	v_readlane_b32 s62, v254, 47
	v_readlane_b32 s63, v254, 48
	v_readlane_b32 s64, v254, 49
	v_readlane_b32 s65, v254, 50
	v_readlane_b32 s66, v254, 51
	v_readlane_b32 s67, v254, 52
	v_readlane_b32 s68, v254, 53
	v_readlane_b32 s69, v254, 54
	v_readlane_b32 s70, v254, 55
	v_readlane_b32 s71, v254, 56
	v_readlane_b32 s72, v254, 57
	v_readlane_b32 s73, v254, 58
	s_add_u32 s2, s0, 0xfffc0080
	s_addc_u32 s3, s1, -1
	s_add_i32 s31, 0, 0x10000
	s_cmp_eq_u32 s30, 12
	s_cselect_b32 s5, s22, s3
	s_cselect_b32 s4, s25, s2
	s_cselect_b32 s3, s26, s29
	s_cselect_b32 s2, s27, s28
	s_add_i32 s33, 0, 0x14000
	s_branch .Lbe_gi_body
.LBB0_152:
	s_barrier
; #define WAIT_V(n) asm volatile("s_waitcnt vmcnt(" #n ")" ::: "memory")
; #define WAIT_L(n) asm volatile("s_waitcnt lgkmcnt(" #n ")" ::: "memory")
; #define BAR __builtin_amdgcn_s_barrier()
; #define SCHED __builtin_amdgcn_sched_barrier(0)
;     ...
;       LDB(B0, 0, 0); LDB(B1, 0, 1); SCHED; LDA(At, 0, 0); STAGE(SAo(1, 1), a1 + hstep, voff);
;       WAIT_V(8); WAIT_L(0); BAR; MMA(0, 0, At, B0); MMA(0, 1, At, B1); BAR; SCHED;
;       LDA(At, 0, 1); STAGE(SBo(0, 0), b2, voffB); STAGE(SBo(0, 1), b2 + hstep, voffB); STAGE(SAo(0, 0), a2, voff);
;       WAIT_V(8); WAIT_L(0); BAR; MMA(1, 0, At, B0); MMA(1, 1, At, B1); BAR; SCHED;
.Lbe_gi_body:
	v_add_u32_e32 v0, s31, v158
	ds_read_b128 v[130:133], v0
	ds_read_b128 v[134:137], v0 offset:1024
	ds_read_b128 v[138:141], v0 offset:2048
	ds_read_b128 v[154:157], v0 offset:3072
	v_add_u32_e32 v0, s33, v158
	ds_read_b128 v[160:163], v0
	ds_read_b128 v[164:167], v0 offset:1024
	ds_read_b128 v[168:171], v0 offset:2048
	ds_read_b128 v[178:181], v0 offset:3072
	v_lshl_add_u64 v[214:215], s[0:1], 0, v[150:151]
	s_add_i32 m0, s9, 0xc000
	ds_read_b128 v[182:185], v159
	ds_read_b128 v[186:189], v159 offset:1024
	ds_read_b128 v[190:193], v159 offset:2048
	ds_read_b128 v[194:197], v159 offset:3072
	ds_read_b128 v[198:201], v159 offset:4096
	ds_read_b128 v[202:205], v159 offset:5120
	ds_read_b128 v[206:209], v159 offset:6144
	ds_read_b128 v[210:213], v159 offset:7168
	global_load_lds_dwordx4 v[214:215], off
	v_lshl_add_u64 v[214:215], s[0:1], 0, v[152:153]
	s_add_i32 m0, s9, 0xe000
	s_nop 0
	global_load_lds_dwordx4 v[214:215], off
	s_waitcnt vmcnt(8)
	s_waitcnt lgkmcnt(0)
	s_barrier
	s_setprio 1
	s_waitcnt lgkmcnt(0)
	v_mfma_f32_16x16x32_bf16 v[126:129], v[130:133], v[182:185], v[126:129]
	v_mfma_f32_16x16x32_bf16 v[122:125], v[138:141], v[182:185], v[122:125]
	v_mfma_f32_16x16x32_bf16 v[110:113], v[130:133], v[190:193], v[110:113]
	v_mfma_f32_16x16x32_bf16 v[106:109], v[138:141], v[190:193], v[106:109]
	v_mfma_f32_16x16x32_bf16 v[94:97], v[130:133], v[198:201], v[94:97]
	v_mfma_f32_16x16x32_bf16 v[90:93], v[138:141], v[198:201], v[90:93]
	v_mfma_f32_16x16x32_bf16 v[78:81], v[130:133], v[206:209], v[78:81]
	v_mfma_f32_16x16x32_bf16 v[74:77], v[138:141], v[206:209], v[74:77]
	v_mfma_f32_16x16x32_bf16 v[126:129], v[134:137], v[186:189], v[126:129]
	v_mfma_f32_16x16x32_bf16 v[122:125], v[154:157], v[186:189], v[122:125]
	v_mfma_f32_16x16x32_bf16 v[110:113], v[134:137], v[194:197], v[110:113]
	v_mfma_f32_16x16x32_bf16 v[106:109], v[154:157], v[194:197], v[106:109]
	v_mfma_f32_16x16x32_bf16 v[94:97], v[134:137], v[202:205], v[94:97]
	v_mfma_f32_16x16x32_bf16 v[90:93], v[154:157], v[202:205], v[90:93]
	v_mfma_f32_16x16x32_bf16 v[78:81], v[134:137], v[210:213], v[78:81]
	v_mfma_f32_16x16x32_bf16 v[74:77], v[154:157], v[210:213], v[74:77]
	s_setprio 0
	s_setprio 1
	v_mfma_f32_16x16x32_bf16 v[118:121], v[160:163], v[182:185], v[118:121]
	v_mfma_f32_16x16x32_bf16 v[114:117], v[168:171], v[182:185], v[114:117]
	v_mfma_f32_16x16x32_bf16 v[102:105], v[160:163], v[190:193], v[102:105]
	v_mfma_f32_16x16x32_bf16 v[98:101], v[168:171], v[190:193], v[98:101]
	v_mfma_f32_16x16x32_bf16 v[86:89], v[160:163], v[198:201], v[86:89]
	v_mfma_f32_16x16x32_bf16 v[82:85], v[168:171], v[198:201], v[82:85]
	v_mfma_f32_16x16x32_bf16 v[70:73], v[160:163], v[206:209], v[70:73]
	v_mfma_f32_16x16x32_bf16 v[66:69], v[168:171], v[206:209], v[66:69]
	v_mfma_f32_16x16x32_bf16 v[118:121], v[164:167], v[186:189], v[118:121]
	v_mfma_f32_16x16x32_bf16 v[114:117], v[178:181], v[186:189], v[114:117]
	v_mfma_f32_16x16x32_bf16 v[102:105], v[164:167], v[194:197], v[102:105]
	v_mfma_f32_16x16x32_bf16 v[98:101], v[178:181], v[194:197], v[98:101]
	v_mfma_f32_16x16x32_bf16 v[86:89], v[164:167], v[202:205], v[86:89]
	v_mfma_f32_16x16x32_bf16 v[82:85], v[178:181], v[202:205], v[82:85]
	v_mfma_f32_16x16x32_bf16 v[70:73], v[164:167], v[210:213], v[70:73]
	v_mfma_f32_16x16x32_bf16 v[66:69], v[178:181], v[210:213], v[66:69]
	s_setprio 0
	s_barrier
	s_add_i32 s31, s31, s8
	v_lshl_add_u64 v[214:215], s[2:3], 0, v[146:147]
	s_mov_b32 m0, s31
	ds_read_b128 v[182:185], v159 offset:16384
	ds_read_b128 v[186:189], v159 offset:17408
	ds_read_b128 v[190:193], v159 offset:18432
	ds_read_b128 v[194:197], v159 offset:19456
	ds_read_b128 v[198:201], v159 offset:20480
	ds_read_b128 v[202:205], v159 offset:21504
	ds_read_b128 v[206:209], v159 offset:22528
	ds_read_b128 v[210:213], v159 offset:23552
	global_load_lds_dwordx4 v[214:215], off
	s_add_i32 m0, s31, 0x2000
	s_add_u32 s40, s2, 0x40000
	v_lshl_add_u64 v[216:217], s[2:3], 0, v[142:143]
	s_addc_u32 s41, s3, 0
	s_add_i32 s31, s33, s8
	global_load_lds_dwordx4 v[216:217], off
	v_lshl_add_u64 v[218:219], s[40:41], 0, v[146:147]
	s_mov_b32 m0, s31
	v_lshl_add_u64 v[220:221], s[4:5], 0, v[144:145]
	global_load_lds_dwordx4 v[218:219], off
	v_lshl_add_u64 v[218:219], s[40:41], 0, v[142:143]
	s_add_i32 m0, s31, 0x2000
	s_nop 0
	global_load_lds_dwordx4 v[218:219], off
	v_lshl_add_u64 v[218:219], s[4:5], 0, v[148:149]
	s_mov_b32 m0, s9
	s_nop 0
	global_load_lds_dwordx4 v[218:219], off
	s_mov_b32 m0, s10
	s_nop 0
	global_load_lds_dwordx4 v[220:221], off
	s_waitcnt vmcnt(8)
	s_waitcnt lgkmcnt(0)
	s_barrier
; #define WAIT_V(n) asm volatile("s_waitcnt vmcnt(" #n ")" ::: "memory")
; #define WAIT_L(n) asm volatile("s_waitcnt lgkmcnt(" #n ")" ::: "memory")
; #define BAR __builtin_amdgcn_s_barrier()
; #define SCHED __builtin_amdgcn_sched_barrier(0)
;     ...
;       WAIT_V(8); WAIT_L(0); BAR; MMA(1, 0, At, B0); MMA(1, 1, At, B1); BAR; SCHED;
;       LDB(B0, 1, 0); LDB(B1, 1, 1); SCHED; LDA(At, 1, 0); STAGE(SAo(0, 1), a2 + hstep, voff);
;       WAIT_V(8); WAIT_L(0); BAR; MMA(0, 0, At, B0); MMA(0, 1, At, B1); BAR; SCHED;
	s_setprio 1
	s_waitcnt lgkmcnt(0)
	v_mfma_f32_16x16x32_bf16 v[62:65], v[130:133], v[182:185], v[62:65]
	v_mfma_f32_16x16x32_bf16 v[58:61], v[138:141], v[182:185], v[58:61]
	v_mfma_f32_16x16x32_bf16 v[46:49], v[130:133], v[190:193], v[46:49]
	v_mfma_f32_16x16x32_bf16 v[42:45], v[138:141], v[190:193], v[42:45]
	v_mfma_f32_16x16x32_bf16 v[30:33], v[130:133], v[198:201], v[30:33]
	v_mfma_f32_16x16x32_bf16 v[26:29], v[138:141], v[198:201], v[26:29]
	v_mfma_f32_16x16x32_bf16 v[14:17], v[130:133], v[206:209], v[14:17]
	v_mfma_f32_16x16x32_bf16 v[10:13], v[138:141], v[206:209], v[10:13]
	v_mfma_f32_16x16x32_bf16 v[62:65], v[134:137], v[186:189], v[62:65]
	v_mfma_f32_16x16x32_bf16 v[58:61], v[154:157], v[186:189], v[58:61]
	v_mfma_f32_16x16x32_bf16 v[46:49], v[134:137], v[194:197], v[46:49]
	v_mfma_f32_16x16x32_bf16 v[42:45], v[154:157], v[194:197], v[42:45]
	v_mfma_f32_16x16x32_bf16 v[30:33], v[134:137], v[202:205], v[30:33]
	v_mfma_f32_16x16x32_bf16 v[26:29], v[154:157], v[202:205], v[26:29]
	v_mfma_f32_16x16x32_bf16 v[14:17], v[134:137], v[210:213], v[14:17]
	v_mfma_f32_16x16x32_bf16 v[10:13], v[154:157], v[210:213], v[10:13]
	s_setprio 0
	s_setprio 1
	v_mfma_f32_16x16x32_bf16 v[54:57], v[160:163], v[182:185], v[54:57]
	v_mfma_f32_16x16x32_bf16 v[50:53], v[168:171], v[182:185], v[50:53]
	v_mfma_f32_16x16x32_bf16 v[38:41], v[160:163], v[190:193], v[38:41]
	v_mfma_f32_16x16x32_bf16 v[34:37], v[168:171], v[190:193], v[34:37]
	v_mfma_f32_16x16x32_bf16 v[22:25], v[160:163], v[198:201], v[22:25]
	v_mfma_f32_16x16x32_bf16 v[18:21], v[168:171], v[198:201], v[18:21]
	v_mfma_f32_16x16x32_bf16 v[6:9], v[160:163], v[206:209], v[6:9]
	v_mfma_f32_16x16x32_bf16 v[2:5], v[168:171], v[206:209], v[2:5]
	v_mfma_f32_16x16x32_bf16 v[54:57], v[164:167], v[186:189], v[54:57]
	v_mfma_f32_16x16x32_bf16 v[50:53], v[178:181], v[186:189], v[50:53]
	v_mfma_f32_16x16x32_bf16 v[38:41], v[164:167], v[194:197], v[38:41]
	v_mfma_f32_16x16x32_bf16 v[34:37], v[178:181], v[194:197], v[34:37]
	v_mfma_f32_16x16x32_bf16 v[22:25], v[164:167], v[202:205], v[22:25]
	v_mfma_f32_16x16x32_bf16 v[18:21], v[178:181], v[202:205], v[18:21]
	v_mfma_f32_16x16x32_bf16 v[6:9], v[164:167], v[210:213], v[6:9]
	v_mfma_f32_16x16x32_bf16 v[2:5], v[178:181], v[210:213], v[2:5]
	s_setprio 0
	s_barrier
	s_add_i32 s31, 0, 0x18000
	v_add_u32_e32 v0, s31, v158
	s_add_i32 s33, 0, 0x1c000
	ds_read_b128 v[130:133], v0
	ds_read_b128 v[134:137], v0 offset:1024
	ds_read_b128 v[138:141], v0 offset:2048
	ds_read_b128 v[154:157], v0 offset:3072
	v_add_u32_e32 v0, s33, v158
	ds_read_b128 v[160:163], v0
	ds_read_b128 v[164:167], v0 offset:1024
	ds_read_b128 v[168:171], v0 offset:2048
	ds_read_b128 v[178:181], v0 offset:3072
	s_add_u32 s4, s4, 0x40000
	s_addc_u32 s5, s5, 0
	s_mov_b32 m0, s11
	v_lshl_add_u64 v[222:223], s[4:5], 0, v[148:149]
	ds_read_b128 v[182:185], v159 offset:32768
	ds_read_b128 v[186:189], v159 offset:33792
	ds_read_b128 v[190:193], v159 offset:34816
	ds_read_b128 v[194:197], v159 offset:35840
	ds_read_b128 v[198:201], v159 offset:36864
	ds_read_b128 v[202:205], v159 offset:37888
	ds_read_b128 v[206:209], v159 offset:38912
	ds_read_b128 v[210:213], v159 offset:39936
	global_load_lds_dwordx4 v[222:223], off
	v_lshl_add_u64 v[222:223], s[4:5], 0, v[144:145]
	s_mov_b32 m0, s12
	s_nop 0
	global_load_lds_dwordx4 v[222:223], off
	s_waitcnt vmcnt(8)
	s_waitcnt lgkmcnt(0)
	s_barrier
	s_setprio 1
	s_waitcnt lgkmcnt(0)
	v_mfma_f32_16x16x32_bf16 v[126:129], v[130:133], v[182:185], v[126:129]
	v_mfma_f32_16x16x32_bf16 v[122:125], v[138:141], v[182:185], v[122:125]
	v_mfma_f32_16x16x32_bf16 v[110:113], v[130:133], v[190:193], v[110:113]
	v_mfma_f32_16x16x32_bf16 v[106:109], v[138:141], v[190:193], v[106:109]
	v_mfma_f32_16x16x32_bf16 v[94:97], v[130:133], v[198:201], v[94:97]
	v_mfma_f32_16x16x32_bf16 v[90:93], v[138:141], v[198:201], v[90:93]
	v_mfma_f32_16x16x32_bf16 v[78:81], v[130:133], v[206:209], v[78:81]
	v_mfma_f32_16x16x32_bf16 v[74:77], v[138:141], v[206:209], v[74:77]
	v_mfma_f32_16x16x32_bf16 v[126:129], v[134:137], v[186:189], v[126:129]
	v_mfma_f32_16x16x32_bf16 v[122:125], v[154:157], v[186:189], v[122:125]
	v_mfma_f32_16x16x32_bf16 v[110:113], v[134:137], v[194:197], v[110:113]
	v_mfma_f32_16x16x32_bf16 v[106:109], v[154:157], v[194:197], v[106:109]
	v_mfma_f32_16x16x32_bf16 v[94:97], v[134:137], v[202:205], v[94:97]
	v_mfma_f32_16x16x32_bf16 v[90:93], v[154:157], v[202:205], v[90:93]
	v_mfma_f32_16x16x32_bf16 v[78:81], v[134:137], v[210:213], v[78:81]
	v_mfma_f32_16x16x32_bf16 v[74:77], v[154:157], v[210:213], v[74:77]
	s_setprio 0
	s_setprio 1
	v_mfma_f32_16x16x32_bf16 v[118:121], v[160:163], v[182:185], v[118:121]
	v_mfma_f32_16x16x32_bf16 v[114:117], v[168:171], v[182:185], v[114:117]
	v_mfma_f32_16x16x32_bf16 v[102:105], v[160:163], v[190:193], v[102:105]
	v_mfma_f32_16x16x32_bf16 v[98:101], v[168:171], v[190:193], v[98:101]
	v_mfma_f32_16x16x32_bf16 v[86:89], v[160:163], v[198:201], v[86:89]
	v_mfma_f32_16x16x32_bf16 v[82:85], v[168:171], v[198:201], v[82:85]
	v_mfma_f32_16x16x32_bf16 v[70:73], v[160:163], v[206:209], v[70:73]
	v_mfma_f32_16x16x32_bf16 v[66:69], v[168:171], v[206:209], v[66:69]
	v_mfma_f32_16x16x32_bf16 v[118:121], v[164:167], v[186:189], v[118:121]
	v_mfma_f32_16x16x32_bf16 v[114:117], v[178:181], v[186:189], v[114:117]
	v_mfma_f32_16x16x32_bf16 v[102:105], v[164:167], v[194:197], v[102:105]
	v_mfma_f32_16x16x32_bf16 v[98:101], v[178:181], v[194:197], v[98:101]
	v_mfma_f32_16x16x32_bf16 v[86:89], v[164:167], v[202:205], v[86:89]
	v_mfma_f32_16x16x32_bf16 v[82:85], v[178:181], v[202:205], v[82:85]
	v_mfma_f32_16x16x32_bf16 v[70:73], v[164:167], v[210:213], v[70:73]
	v_mfma_f32_16x16x32_bf16 v[66:69], v[178:181], v[210:213], v[66:69]
	s_setprio 0
	s_barrier
; #define WAIT_V(n) asm volatile("s_waitcnt vmcnt(" #n ")" ::: "memory")
; #define WAIT_L(n) asm volatile("s_waitcnt lgkmcnt(" #n ")" ::: "memory")
; #define BAR __builtin_amdgcn_s_barrier()
; #define SCHED __builtin_amdgcn_sched_barrier(0)
;     ...
;       LDA(At, 1, 1); STAGE(SBo(1, 0), b3, voffB); STAGE(SBo(1, 1), b3 + hstep, voffB); STAGE(SAo(1, 0), a3, voff);
;       WAIT_V(8); WAIT_L(0); BAR; MMA(1, 0, At, B0); MMA(1, 1, At, B1); BAR; SCHED;
;     }
;     if (wr == 0) BAR;
	s_add_i32 s4, s31, s8
	v_lshl_add_u64 v[214:215], v[214:215], 0, s[34:35]
	s_mov_b32 m0, s4
	ds_read_b128 v[182:185], v159 offset:49152
	ds_read_b128 v[186:189], v159 offset:50176
	ds_read_b128 v[190:193], v159 offset:51200
	ds_read_b128 v[194:197], v159 offset:52224
	ds_read_b128 v[198:201], v159 offset:53248
	ds_read_b128 v[202:205], v159 offset:54272
	ds_read_b128 v[206:209], v159 offset:55296
	ds_read_b128 v[210:213], v159 offset:56320
	global_load_lds_dwordx4 v[214:215], off
	s_add_i32 m0, s4, 0x2000
	s_add_u32 s2, s2, 0x40080
	v_lshl_add_u64 v[214:215], v[216:217], 0, s[34:35]
	s_addc_u32 s3, s3, 0
	s_add_i32 s4, s33, s8
	global_load_lds_dwordx4 v[214:215], off
	v_lshl_add_u64 v[214:215], s[2:3], 0, v[146:147]
	s_mov_b32 m0, s4
	s_nop 0
	global_load_lds_dwordx4 v[214:215], off
	v_lshl_add_u64 v[214:215], s[2:3], 0, v[142:143]
	s_add_i32 m0, s4, 0x2000
	s_nop 0
	global_load_lds_dwordx4 v[214:215], off
	v_lshl_add_u64 v[214:215], v[218:219], 0, s[34:35]
	s_mov_b32 m0, s15
	s_nop 0
	global_load_lds_dwordx4 v[214:215], off
	v_lshl_add_u64 v[214:215], v[220:221], 0, s[34:35]
	s_mov_b32 m0, s16
	s_nop 0
	global_load_lds_dwordx4 v[214:215], off
	s_waitcnt vmcnt(8)
	s_waitcnt lgkmcnt(0)
	s_barrier
	s_setprio 1
	s_waitcnt lgkmcnt(0)
	v_mfma_f32_16x16x32_bf16 v[62:65], v[130:133], v[182:185], v[62:65]
	v_mfma_f32_16x16x32_bf16 v[58:61], v[138:141], v[182:185], v[58:61]
	v_mfma_f32_16x16x32_bf16 v[46:49], v[130:133], v[190:193], v[46:49]
	v_mfma_f32_16x16x32_bf16 v[42:45], v[138:141], v[190:193], v[42:45]
	v_mfma_f32_16x16x32_bf16 v[30:33], v[130:133], v[198:201], v[30:33]
	v_mfma_f32_16x16x32_bf16 v[26:29], v[138:141], v[198:201], v[26:29]
	v_mfma_f32_16x16x32_bf16 v[14:17], v[130:133], v[206:209], v[14:17]
	v_mfma_f32_16x16x32_bf16 v[10:13], v[138:141], v[206:209], v[10:13]
	v_mfma_f32_16x16x32_bf16 v[62:65], v[134:137], v[186:189], v[62:65]
	v_mfma_f32_16x16x32_bf16 v[58:61], v[154:157], v[186:189], v[58:61]
	v_mfma_f32_16x16x32_bf16 v[46:49], v[134:137], v[194:197], v[46:49]
	v_mfma_f32_16x16x32_bf16 v[42:45], v[154:157], v[194:197], v[42:45]
	v_mfma_f32_16x16x32_bf16 v[30:33], v[134:137], v[202:205], v[30:33]
	v_mfma_f32_16x16x32_bf16 v[26:29], v[154:157], v[202:205], v[26:29]
	v_mfma_f32_16x16x32_bf16 v[14:17], v[134:137], v[210:213], v[14:17]
	v_mfma_f32_16x16x32_bf16 v[10:13], v[154:157], v[210:213], v[10:13]
	s_setprio 0
	s_setprio 1
	v_mfma_f32_16x16x32_bf16 v[54:57], v[160:163], v[182:185], v[54:57]
	v_mfma_f32_16x16x32_bf16 v[50:53], v[168:171], v[182:185], v[50:53]
	v_mfma_f32_16x16x32_bf16 v[38:41], v[160:163], v[190:193], v[38:41]
	v_mfma_f32_16x16x32_bf16 v[34:37], v[168:171], v[190:193], v[34:37]
	v_mfma_f32_16x16x32_bf16 v[22:25], v[160:163], v[198:201], v[22:25]
	v_mfma_f32_16x16x32_bf16 v[18:21], v[168:171], v[198:201], v[18:21]
	v_mfma_f32_16x16x32_bf16 v[6:9], v[160:163], v[206:209], v[6:9]
	v_mfma_f32_16x16x32_bf16 v[2:5], v[168:171], v[206:209], v[2:5]
	v_mfma_f32_16x16x32_bf16 v[54:57], v[164:167], v[186:189], v[54:57]
	v_mfma_f32_16x16x32_bf16 v[50:53], v[178:181], v[186:189], v[50:53]
	v_mfma_f32_16x16x32_bf16 v[38:41], v[164:167], v[194:197], v[38:41]
	v_mfma_f32_16x16x32_bf16 v[34:37], v[178:181], v[194:197], v[34:37]
	v_mfma_f32_16x16x32_bf16 v[22:25], v[164:167], v[202:205], v[22:25]
	v_mfma_f32_16x16x32_bf16 v[18:21], v[178:181], v[202:205], v[18:21]
	v_mfma_f32_16x16x32_bf16 v[6:9], v[164:167], v[210:213], v[6:9]
	v_mfma_f32_16x16x32_bf16 v[2:5], v[178:181], v[210:213], v[2:5]
	s_setprio 0
	s_add_i32 s30, s30, 2
	s_add_u32 s0, s0, 0x100
	s_addc_u32 s1, s1, 0
	s_add_u32 s28, s28, 0x100
	s_addc_u32 s29, s29, 0
	s_cmp_gt_u32 s30, 13
	s_cbranch_scc1 .Lbe_gi_exit
	s_add_u32 s2, s0, 0xfffc0080
	s_addc_u32 s3, s1, -1
	s_add_i32 s31, 0, 0x10000
	s_cmp_eq_u32 s30, 12
	s_cselect_b32 s5, s22, s3
	s_cselect_b32 s4, s25, s2
	s_cselect_b32 s3, s26, s29
	s_cselect_b32 s2, s27, s28
	s_add_i32 s33, 0, 0x14000
	s_branch .LBB0_152
.Lbe_gi_exit:
	s_barrier
	s_and_b64 vcc, exec, s[46:47]
	s_cbranch_vccz .LBB0_155
	s_barrier

;     ...
;     const bool has_next = unit(ui + 1, npm, npn, nkq);
;     const char* nA = has_next ? (const char*)A + (size_t)npm * tstep + (nkq > 0 ? (size_t)nkq * (K / 4) * 2 : 0) : cA;
;     const char* nB = has_next ? (const char*)Bt + (size_t)npn * tstep + (nkq > 0 ? (size_t)nkq * (K / 4) * 2 : 0) : cB;
;     const int ntu = (SPLIT && kq >= 0) ? nt / 4 : nt;
;     for (int t = 0; t < ntu; t += 2) {
;       const bool last = (t == ntu - 2);
;       const char* a1 = cA + (size_t)(t + 1) * kstep;
;       const char* a2 = last ? nA : cA + (size_t)(t + 2) * kstep;
;       const char* b2 = last ? nB : cB + (size_t)(t + 2) * kstep;
;     ...
;     for (int a = 0; a < 2; ++a)
; #pragma unroll
;       for (int b = 0; b < 2; ++b)
; #pragma unroll
;         for (int m = 0; m < 4; ++m)
; #pragma unroll
;           for (int n = 0; n < 2; ++n) acc[a][b][m][n] = (f32x4){0.f, 0.f, 0.f, 0.f};
;     pm = npm; pn = npn; kq = nkq; cA = nA; cB = nB; ++ui;
.LBB0_905:
	s_nop 0
	v_readlane_b32 s10, v254, 34
	v_readlane_b32 s11, v254, 35
	v_readlane_b32 s60, v254, 45
	s_lshl_b64 s[10:11], s[10:11], 19
	v_readlane_b32 s74, v254, 59
	v_readlane_b32 s75, v254, 60
	s_add_u32 s10, s74, s10
	s_addc_u32 s11, s75, s11
	s_and_b64 s[12:13], s[0:1], exec
	s_cselect_b32 s17, s11, s15
	s_cselect_b32 s19, s10, s14
	s_ashr_i32 s9, s8, 31
	s_lshl_b64 s[12:13], s[8:9], 19
	s_add_u32 s12, s24, s12
	s_addc_u32 s13, s25, s13
	s_and_b64 s[22:23], s[0:1], exec
	s_cselect_b32 s9, s13, s21
	s_cselect_b32 s49, s12, s20
	s_add_u32 s14, s14, 0x40080
	s_addc_u32 s15, s15, 0
	s_add_u32 s50, s20, 0x100
	v_mov_b32_e32 v2, 0
	s_addc_u32 s51, s21, 0
	s_mov_b32 s52, -2
	v_mov_b32_e32 v3, v2
	v_mov_b32_e32 v4, v2
	v_mov_b32_e32 v5, v2
	v_mov_b32_e32 v6, v2
	v_mov_b32_e32 v7, v2
	v_mov_b32_e32 v8, v2
	v_mov_b32_e32 v9, v2
	v_mov_b32_e32 v18, v2
	v_mov_b32_e32 v19, v2
	v_mov_b32_e32 v20, v2
	v_mov_b32_e32 v21, v2
	v_mov_b32_e32 v22, v2
	v_mov_b32_e32 v23, v2
	v_mov_b32_e32 v24, v2
	v_mov_b32_e32 v25, v2
	v_mov_b32_e32 v34, v2
	v_mov_b32_e32 v35, v2
	v_mov_b32_e32 v36, v2
	v_mov_b32_e32 v37, v2
	v_mov_b32_e32 v38, v2
	v_mov_b32_e32 v39, v2
	v_mov_b32_e32 v40, v2
	v_mov_b32_e32 v41, v2
	v_mov_b32_e32 v50, v2
	v_mov_b32_e32 v51, v2
	v_mov_b32_e32 v52, v2
	v_mov_b32_e32 v53, v2
	v_mov_b32_e32 v54, v2
	v_mov_b32_e32 v55, v2
	v_mov_b32_e32 v56, v2
	v_mov_b32_e32 v57, v2
	v_mov_b32_e32 v10, v2
	v_mov_b32_e32 v11, v2
	v_mov_b32_e32 v12, v2
	v_mov_b32_e32 v13, v2
	v_mov_b32_e32 v14, v2
	v_mov_b32_e32 v15, v2
	v_mov_b32_e32 v16, v2
	v_mov_b32_e32 v17, v2
	v_mov_b32_e32 v26, v2
	v_mov_b32_e32 v27, v2
	v_mov_b32_e32 v28, v2
	v_mov_b32_e32 v29, v2
	v_mov_b32_e32 v30, v2
	v_mov_b32_e32 v31, v2
	v_mov_b32_e32 v32, v2
	v_mov_b32_e32 v33, v2
	v_mov_b32_e32 v42, v2
	v_mov_b32_e32 v43, v2
	v_mov_b32_e32 v44, v2
	v_mov_b32_e32 v45, v2
	v_mov_b32_e32 v46, v2
	v_mov_b32_e32 v47, v2
	v_mov_b32_e32 v48, v2
	v_mov_b32_e32 v49, v2
	v_mov_b32_e32 v58, v2
	v_mov_b32_e32 v59, v2
	v_mov_b32_e32 v60, v2
	v_mov_b32_e32 v61, v2
	v_mov_b32_e32 v62, v2
	v_mov_b32_e32 v63, v2
	v_mov_b32_e32 v64, v2
	v_mov_b32_e32 v65, v2
	v_mov_b32_e32 v66, v2
	v_mov_b32_e32 v67, v2
	v_mov_b32_e32 v68, v2
	v_mov_b32_e32 v69, v2
	v_mov_b32_e32 v70, v2
	v_mov_b32_e32 v71, v2
	v_mov_b32_e32 v72, v2
	v_mov_b32_e32 v73, v2
	v_mov_b32_e32 v82, v2
	v_mov_b32_e32 v83, v2
	v_mov_b32_e32 v84, v2
	v_mov_b32_e32 v85, v2
	v_mov_b32_e32 v86, v2
	v_mov_b32_e32 v87, v2
	v_mov_b32_e32 v88, v2
	v_mov_b32_e32 v89, v2
	s_waitcnt vmcnt(0)
	v_mov_b32_e32 v98, v2
	v_mov_b32_e32 v99, v2
	v_mov_b32_e32 v100, v2
	v_mov_b32_e32 v101, v2
	v_mov_b32_e32 v102, v2
	v_mov_b32_e32 v103, v2
	v_mov_b32_e32 v104, v2
	v_mov_b32_e32 v105, v2
	v_mov_b32_e32 v126, v2
	v_mov_b32_e32 v127, v2
	v_mov_b32_e32 v128, v2
	v_mov_b32_e32 v129, v2
	v_mov_b32_e32 v134, v2
	v_mov_b32_e32 v135, v2
	v_mov_b32_e32 v136, v2
	v_mov_b32_e32 v137, v2
	v_mov_b32_e32 v74, v2
	v_mov_b32_e32 v75, v2
	v_mov_b32_e32 v76, v2
	v_mov_b32_e32 v77, v2
	v_mov_b32_e32 v78, v2
	v_mov_b32_e32 v79, v2
	v_mov_b32_e32 v80, v2
	v_mov_b32_e32 v81, v2
	v_mov_b32_e32 v90, v2
	v_mov_b32_e32 v91, v2
	v_mov_b32_e32 v92, v2
	v_mov_b32_e32 v93, v2
	v_mov_b32_e32 v94, v2
	v_mov_b32_e32 v95, v2
	v_mov_b32_e32 v96, v2
	v_mov_b32_e32 v97, v2
	v_mov_b32_e32 v110, v2
	v_mov_b32_e32 v111, v2
	v_mov_b32_e32 v112, v2
	v_mov_b32_e32 v113, v2
	v_mov_b32_e32 v122, v2
	v_mov_b32_e32 v123, v2
	v_mov_b32_e32 v124, v2
	v_mov_b32_e32 v125, v2
	v_mov_b32_e32 v138, v2
	v_mov_b32_e32 v139, v2
	v_mov_b32_e32 v140, v2
	v_mov_b32_e32 v141, v2
	v_mov_b32_e32 v142, v2
	v_mov_b32_e32 v143, v2
	v_mov_b32_e32 v144, v2
	v_mov_b32_e32 v145, v2
	v_readlane_b32 s61, v254, 46
	v_readlane_b32 s62, v254, 47
	v_readlane_b32 s63, v254, 48
	v_readlane_b32 s64, v254, 49
	v_readlane_b32 s65, v254, 50
	v_readlane_b32 s66, v254, 51
	v_readlane_b32 s67, v254, 52
	v_readlane_b32 s68, v254, 53
	v_readlane_b32 s69, v254, 54
	v_readlane_b32 s70, v254, 55
	v_readlane_b32 s71, v254, 56
	v_readlane_b32 s72, v254, 57
	v_readlane_b32 s73, v254, 58
	s_add_u32 s20, s14, 0xfffc0080
	s_addc_u32 s21, s15, -1
	s_add_i32 s53, 0, 0x10000
	s_cmp_eq_u32 s52, 12
	s_cselect_b32 s23, s17, s21
	s_cselect_b32 s22, s19, s20
	s_cselect_b32 s21, s9, s51
	s_cselect_b32 s20, s49, s50
	s_add_i32 s56, 0, 0x14000
	s_branch .Lbe_go_body

; #define WAIT_V(n) asm volatile("s_waitcnt vmcnt(" #n ")" ::: "memory")
; #define WAIT_L(n) asm volatile("s_waitcnt lgkmcnt(" #n ")" ::: "memory")
; #define BAR __builtin_amdgcn_s_barrier()
; #define SCHED __builtin_amdgcn_sched_barrier(0)
;     ...
;       LDB(B0, 0, 0); LDB(B1, 0, 1); SCHED; LDA(At, 0, 0); STAGE(SAo(1, 1), a1 + hstep, voff);
;       WAIT_V(8); WAIT_L(0); BAR; MMA(0, 0, At, B0); MMA(0, 1, At, B1); BAR; SCHED;
;       LDA(At, 0, 1); STAGE(SBo(0, 0), b2, voffB); STAGE(SBo(0, 1), b2 + hstep, voffB); STAGE(SAo(0, 0), a2, voff);
;       WAIT_V(8); WAIT_L(0); BAR; MMA(1, 0, At, B0); MMA(1, 1, At, B1); BAR; SCHED;
.Lbe_go_body:
	v_add_u32_e32 v130, s53, v206
	v_add_u32_e32 v158, s56, v206
	ds_read_b128 v[106:109], v130
	ds_read_b128 v[114:117], v130 offset:1024
	ds_read_b128 v[118:121], v130 offset:2048
	ds_read_b128 v[130:133], v130 offset:3072
	ds_read_b128 v[146:149], v158
	ds_read_b128 v[150:153], v158 offset:1024
	ds_read_b128 v[154:157], v158 offset:2048
	ds_read_b128 v[158:161], v158 offset:3072
	v_lshl_add_u64 v[212:213], s[14:15], 0, v[168:169]
	s_add_i32 m0, s27, 0xc000
	ds_read_b128 v[178:181], v207
	ds_read_b128 v[182:185], v207 offset:1024
	ds_read_b128 v[186:189], v207 offset:2048
	ds_read_b128 v[190:193], v207 offset:3072
	ds_read_b128 v[194:197], v207 offset:4096
	ds_read_b128 v[198:201], v207 offset:5120
	ds_read_b128 v[202:205], v207 offset:6144
	ds_read_b128 v[208:211], v207 offset:7168
	global_load_lds_dwordx4 v[212:213], off
	v_lshl_add_u64 v[212:213], s[14:15], 0, v[170:171]
	s_add_i32 m0, s27, 0xe000
	s_nop 0
	global_load_lds_dwordx4 v[212:213], off
	s_waitcnt vmcnt(8)
	s_waitcnt lgkmcnt(0)
	s_barrier
	s_setprio 1
	s_waitcnt lgkmcnt(0)
	v_mfma_f32_16x16x32_bf16 v[142:145], v[106:109], v[178:181], v[142:145]
	v_mfma_f32_16x16x32_bf16 v[138:141], v[118:121], v[178:181], v[138:141]
	v_mfma_f32_16x16x32_bf16 v[122:125], v[106:109], v[186:189], v[122:125]
	v_mfma_f32_16x16x32_bf16 v[110:113], v[118:121], v[186:189], v[110:113]
	v_mfma_f32_16x16x32_bf16 v[94:97], v[106:109], v[194:197], v[94:97]
	v_mfma_f32_16x16x32_bf16 v[90:93], v[118:121], v[194:197], v[90:93]
	v_mfma_f32_16x16x32_bf16 v[78:81], v[106:109], v[202:205], v[78:81]
	v_mfma_f32_16x16x32_bf16 v[74:77], v[118:121], v[202:205], v[74:77]
	v_mfma_f32_16x16x32_bf16 v[142:145], v[114:117], v[182:185], v[142:145]
	v_mfma_f32_16x16x32_bf16 v[138:141], v[130:133], v[182:185], v[138:141]
	v_mfma_f32_16x16x32_bf16 v[122:125], v[114:117], v[190:193], v[122:125]
	v_mfma_f32_16x16x32_bf16 v[110:113], v[130:133], v[190:193], v[110:113]
	v_mfma_f32_16x16x32_bf16 v[94:97], v[114:117], v[198:201], v[94:97]
	v_mfma_f32_16x16x32_bf16 v[90:93], v[130:133], v[198:201], v[90:93]
	v_mfma_f32_16x16x32_bf16 v[78:81], v[114:117], v[208:211], v[78:81]
	v_mfma_f32_16x16x32_bf16 v[74:77], v[130:133], v[208:211], v[74:77]
	s_setprio 0
	s_setprio 1
	v_mfma_f32_16x16x32_bf16 v[134:137], v[146:149], v[178:181], v[134:137]
	v_mfma_f32_16x16x32_bf16 v[126:129], v[154:157], v[178:181], v[126:129]
	v_mfma_f32_16x16x32_bf16 v[102:105], v[146:149], v[186:189], v[102:105]
	v_mfma_f32_16x16x32_bf16 v[98:101], v[154:157], v[186:189], v[98:101]
	v_mfma_f32_16x16x32_bf16 v[86:89], v[146:149], v[194:197], v[86:89]
	v_mfma_f32_16x16x32_bf16 v[82:85], v[154:157], v[194:197], v[82:85]
	v_mfma_f32_16x16x32_bf16 v[70:73], v[146:149], v[202:205], v[70:73]
	v_mfma_f32_16x16x32_bf16 v[66:69], v[154:157], v[202:205], v[66:69]
	v_mfma_f32_16x16x32_bf16 v[134:137], v[150:153], v[182:185], v[134:137]
	v_mfma_f32_16x16x32_bf16 v[126:129], v[158:161], v[182:185], v[126:129]
	v_mfma_f32_16x16x32_bf16 v[102:105], v[150:153], v[190:193], v[102:105]
	v_mfma_f32_16x16x32_bf16 v[98:101], v[158:161], v[190:193], v[98:101]
	v_mfma_f32_16x16x32_bf16 v[86:89], v[150:153], v[198:201], v[86:89]
	v_mfma_f32_16x16x32_bf16 v[82:85], v[158:161], v[198:201], v[82:85]
	v_mfma_f32_16x16x32_bf16 v[70:73], v[150:153], v[208:211], v[70:73]
	v_mfma_f32_16x16x32_bf16 v[66:69], v[158:161], v[208:211], v[66:69]
	s_setprio 0
	s_barrier
	s_add_i32 s53, s53, s26
	v_lshl_add_u64 v[212:213], s[20:21], 0, v[0:1]
	s_mov_b32 m0, s53
	ds_read_b128 v[178:181], v207 offset:16384
	ds_read_b128 v[182:185], v207 offset:17408
	ds_read_b128 v[186:189], v207 offset:18432
	ds_read_b128 v[190:193], v207 offset:19456
	ds_read_b128 v[194:197], v207 offset:20480
	ds_read_b128 v[198:201], v207 offset:21504
	ds_read_b128 v[202:205], v207 offset:22528
	ds_read_b128 v[208:211], v207 offset:23552
	global_load_lds_dwordx4 v[212:213], off
	s_add_i32 m0, s53, 0x2000
	s_add_u32 s54, s20, 0x40000
	v_lshl_add_u64 v[214:215], s[20:21], 0, v[166:167]
	s_addc_u32 s55, s21, 0
	s_add_i32 s53, s56, s26
	global_load_lds_dwordx4 v[214:215], off
	v_lshl_add_u64 v[216:217], s[54:55], 0, v[0:1]
	s_mov_b32 m0, s53
	v_lshl_add_u64 v[218:219], s[22:23], 0, v[164:165]
	global_load_lds_dwordx4 v[216:217], off
	v_lshl_add_u64 v[216:217], s[54:55], 0, v[166:167]
	s_add_i32 m0, s53, 0x2000
	s_nop 0
	global_load_lds_dwordx4 v[216:217], off
	v_lshl_add_u64 v[216:217], s[22:23], 0, v[162:163]
	s_mov_b32 m0, s27
	s_nop 0
	global_load_lds_dwordx4 v[216:217], off
	s_mov_b32 m0, s29
	s_nop 0
	global_load_lds_dwordx4 v[218:219], off
	s_waitcnt vmcnt(8)
	s_waitcnt lgkmcnt(0)
	s_barrier
; #define WAIT_V(n) asm volatile("s_waitcnt vmcnt(" #n ")" ::: "memory")
; #define WAIT_L(n) asm volatile("s_waitcnt lgkmcnt(" #n ")" ::: "memory")
; #define BAR __builtin_amdgcn_s_barrier()
; #define SCHED __builtin_amdgcn_sched_barrier(0)
;     ...
;       WAIT_V(8); WAIT_L(0); BAR; MMA(1, 0, At, B0); MMA(1, 1, At, B1); BAR; SCHED;
;       LDB(B0, 1, 0); LDB(B1, 1, 1); SCHED; LDA(At, 1, 0); STAGE(SAo(0, 1), a2 + hstep, voff);
;       WAIT_V(8); WAIT_L(0); BAR; MMA(0, 0, At, B0); MMA(0, 1, At, B1); BAR; SCHED;
	s_setprio 1
	s_waitcnt lgkmcnt(0)
	v_mfma_f32_16x16x32_bf16 v[62:65], v[106:109], v[178:181], v[62:65]
	v_mfma_f32_16x16x32_bf16 v[58:61], v[118:121], v[178:181], v[58:61]
	v_mfma_f32_16x16x32_bf16 v[46:49], v[106:109], v[186:189], v[46:49]
	v_mfma_f32_16x16x32_bf16 v[42:45], v[118:121], v[186:189], v[42:45]
	v_mfma_f32_16x16x32_bf16 v[30:33], v[106:109], v[194:197], v[30:33]
	v_mfma_f32_16x16x32_bf16 v[26:29], v[118:121], v[194:197], v[26:29]
	v_mfma_f32_16x16x32_bf16 v[14:17], v[106:109], v[202:205], v[14:17]
	v_mfma_f32_16x16x32_bf16 v[10:13], v[118:121], v[202:205], v[10:13]
	v_mfma_f32_16x16x32_bf16 v[62:65], v[114:117], v[182:185], v[62:65]
	v_mfma_f32_16x16x32_bf16 v[58:61], v[130:133], v[182:185], v[58:61]
	v_mfma_f32_16x16x32_bf16 v[46:49], v[114:117], v[190:193], v[46:49]
	v_mfma_f32_16x16x32_bf16 v[42:45], v[130:133], v[190:193], v[42:45]
	v_mfma_f32_16x16x32_bf16 v[30:33], v[114:117], v[198:201], v[30:33]
	v_mfma_f32_16x16x32_bf16 v[26:29], v[130:133], v[198:201], v[26:29]
	v_mfma_f32_16x16x32_bf16 v[14:17], v[114:117], v[208:211], v[14:17]
	v_mfma_f32_16x16x32_bf16 v[10:13], v[130:133], v[208:211], v[10:13]
	s_setprio 0
	s_setprio 1
	v_mfma_f32_16x16x32_bf16 v[54:57], v[146:149], v[178:181], v[54:57]
	v_mfma_f32_16x16x32_bf16 v[50:53], v[154:157], v[178:181], v[50:53]
	v_mfma_f32_16x16x32_bf16 v[38:41], v[146:149], v[186:189], v[38:41]
	v_mfma_f32_16x16x32_bf16 v[34:37], v[154:157], v[186:189], v[34:37]
	v_mfma_f32_16x16x32_bf16 v[22:25], v[146:149], v[194:197], v[22:25]
	v_mfma_f32_16x16x32_bf16 v[18:21], v[154:157], v[194:197], v[18:21]
	v_mfma_f32_16x16x32_bf16 v[6:9], v[146:149], v[202:205], v[6:9]
	v_mfma_f32_16x16x32_bf16 v[2:5], v[154:157], v[202:205], v[2:5]
	v_mfma_f32_16x16x32_bf16 v[54:57], v[150:153], v[182:185], v[54:57]
	v_mfma_f32_16x16x32_bf16 v[50:53], v[158:161], v[182:185], v[50:53]
	v_mfma_f32_16x16x32_bf16 v[38:41], v[150:153], v[190:193], v[38:41]
	v_mfma_f32_16x16x32_bf16 v[34:37], v[158:161], v[190:193], v[34:37]
	v_mfma_f32_16x16x32_bf16 v[22:25], v[150:153], v[198:201], v[22:25]
	v_mfma_f32_16x16x32_bf16 v[18:21], v[158:161], v[198:201], v[18:21]
	v_mfma_f32_16x16x32_bf16 v[6:9], v[150:153], v[208:211], v[6:9]
	v_mfma_f32_16x16x32_bf16 v[2:5], v[158:161], v[208:211], v[2:5]
	s_setprio 0
	s_barrier
	s_add_i32 s53, 0, 0x18000
	s_add_i32 s54, 0, 0x1c000
	v_add_u32_e32 v130, s53, v206
	v_add_u32_e32 v158, s54, v206
	ds_read_b128 v[106:109], v130
	ds_read_b128 v[114:117], v130 offset:1024
	ds_read_b128 v[118:121], v130 offset:2048
	ds_read_b128 v[130:133], v130 offset:3072
	ds_read_b128 v[146:149], v158
	ds_read_b128 v[150:153], v158 offset:1024
	ds_read_b128 v[154:157], v158 offset:2048
	ds_read_b128 v[158:161], v158 offset:3072
	s_add_u32 s22, s22, 0x40000
	s_addc_u32 s23, s23, 0
	s_mov_b32 m0, s30
	v_lshl_add_u64 v[220:221], s[22:23], 0, v[162:163]
	ds_read_b128 v[178:181], v207 offset:32768
	ds_read_b128 v[182:185], v207 offset:33792
	ds_read_b128 v[186:189], v207 offset:34816
	ds_read_b128 v[190:193], v207 offset:35840
	ds_read_b128 v[194:197], v207 offset:36864
	ds_read_b128 v[198:201], v207 offset:37888
	ds_read_b128 v[202:205], v207 offset:38912
	ds_read_b128 v[208:211], v207 offset:39936
	global_load_lds_dwordx4 v[220:221], off
	v_lshl_add_u64 v[220:221], s[22:23], 0, v[164:165]
	s_mov_b32 m0, s31
	s_nop 0
	global_load_lds_dwordx4 v[220:221], off
	s_waitcnt vmcnt(8)
	s_waitcnt lgkmcnt(0)
	s_barrier
	s_setprio 1
	s_waitcnt lgkmcnt(0)
	v_mfma_f32_16x16x32_bf16 v[142:145], v[106:109], v[178:181], v[142:145]
	v_mfma_f32_16x16x32_bf16 v[138:141], v[118:121], v[178:181], v[138:141]
	v_mfma_f32_16x16x32_bf16 v[122:125], v[106:109], v[186:189], v[122:125]
	v_mfma_f32_16x16x32_bf16 v[110:113], v[118:121], v[186:189], v[110:113]
	v_mfma_f32_16x16x32_bf16 v[94:97], v[106:109], v[194:197], v[94:97]
	v_mfma_f32_16x16x32_bf16 v[90:93], v[118:121], v[194:197], v[90:93]
	v_mfma_f32_16x16x32_bf16 v[78:81], v[106:109], v[202:205], v[78:81]
	v_mfma_f32_16x16x32_bf16 v[74:77], v[118:121], v[202:205], v[74:77]
	v_mfma_f32_16x16x32_bf16 v[142:145], v[114:117], v[182:185], v[142:145]
	v_mfma_f32_16x16x32_bf16 v[138:141], v[130:133], v[182:185], v[138:141]
	v_mfma_f32_16x16x32_bf16 v[122:125], v[114:117], v[190:193], v[122:125]
	v_mfma_f32_16x16x32_bf16 v[110:113], v[130:133], v[190:193], v[110:113]
	v_mfma_f32_16x16x32_bf16 v[94:97], v[114:117], v[198:201], v[94:97]
	v_mfma_f32_16x16x32_bf16 v[90:93], v[130:133], v[198:201], v[90:93]
	v_mfma_f32_16x16x32_bf16 v[78:81], v[114:117], v[208:211], v[78:81]
	v_mfma_f32_16x16x32_bf16 v[74:77], v[130:133], v[208:211], v[74:77]
	s_setprio 0
	s_setprio 1
	v_mfma_f32_16x16x32_bf16 v[134:137], v[146:149], v[178:181], v[134:137]
	v_mfma_f32_16x16x32_bf16 v[126:129], v[154:157], v[178:181], v[126:129]
	v_mfma_f32_16x16x32_bf16 v[102:105], v[146:149], v[186:189], v[102:105]
	v_mfma_f32_16x16x32_bf16 v[98:101], v[154:157], v[186:189], v[98:101]
	v_mfma_f32_16x16x32_bf16 v[86:89], v[146:149], v[194:197], v[86:89]
	v_mfma_f32_16x16x32_bf16 v[82:85], v[154:157], v[194:197], v[82:85]
	v_mfma_f32_16x16x32_bf16 v[70:73], v[146:149], v[202:205], v[70:73]
	v_mfma_f32_16x16x32_bf16 v[66:69], v[154:157], v[202:205], v[66:69]
	v_mfma_f32_16x16x32_bf16 v[134:137], v[150:153], v[182:185], v[134:137]
	v_mfma_f32_16x16x32_bf16 v[126:129], v[158:161], v[182:185], v[126:129]
	v_mfma_f32_16x16x32_bf16 v[102:105], v[150:153], v[190:193], v[102:105]
	v_mfma_f32_16x16x32_bf16 v[98:101], v[158:161], v[190:193], v[98:101]
	v_mfma_f32_16x16x32_bf16 v[86:89], v[150:153], v[198:201], v[86:89]
	v_mfma_f32_16x16x32_bf16 v[82:85], v[158:161], v[198:201], v[82:85]
	v_mfma_f32_16x16x32_bf16 v[70:73], v[150:153], v[208:211], v[70:73]
	v_mfma_f32_16x16x32_bf16 v[66:69], v[158:161], v[208:211], v[66:69]
	s_setprio 0
	s_barrier
; #define WAIT_V(n) asm volatile("s_waitcnt vmcnt(" #n ")" ::: "memory")
; #define WAIT_L(n) asm volatile("s_waitcnt lgkmcnt(" #n ")" ::: "memory")
; #define BAR __builtin_amdgcn_s_barrier()
; #define SCHED __builtin_amdgcn_sched_barrier(0)
;     ...
;       LDA(At, 1, 1); STAGE(SBo(1, 0), b3, voffB); STAGE(SBo(1, 1), b3 + hstep, voffB); STAGE(SAo(1, 0), a3, voff);
;       WAIT_V(8); WAIT_L(0); BAR; MMA(1, 0, At, B0); MMA(1, 1, At, B1); BAR; SCHED;
;     }
;     if (wr == 0) BAR;
	s_add_i32 s22, s53, s26
	v_lshl_add_u64 v[212:213], v[212:213], 0, s[34:35]
	s_mov_b32 m0, s22
	ds_read_b128 v[178:181], v207 offset:49152
	ds_read_b128 v[182:185], v207 offset:50176
	ds_read_b128 v[186:189], v207 offset:51200
	ds_read_b128 v[190:193], v207 offset:52224
	ds_read_b128 v[194:197], v207 offset:53248
	ds_read_b128 v[198:201], v207 offset:54272
	ds_read_b128 v[202:205], v207 offset:55296
	ds_read_b128 v[208:211], v207 offset:56320
	global_load_lds_dwordx4 v[212:213], off
	s_add_i32 m0, s22, 0x2000
	s_add_u32 s20, s20, 0x40080
	v_lshl_add_u64 v[212:213], v[214:215], 0, s[34:35]
	s_addc_u32 s21, s21, 0
	s_add_i32 s22, s54, s26
	global_load_lds_dwordx4 v[212:213], off
	v_lshl_add_u64 v[212:213], s[20:21], 0, v[0:1]
	s_mov_b32 m0, s22
	s_nop 0
	global_load_lds_dwordx4 v[212:213], off
	v_lshl_add_u64 v[212:213], s[20:21], 0, v[166:167]
	s_add_i32 m0, s22, 0x2000
	s_nop 0
	global_load_lds_dwordx4 v[212:213], off
	v_lshl_add_u64 v[212:213], v[216:217], 0, s[34:35]
	s_mov_b32 m0, s44
	s_nop 0
	global_load_lds_dwordx4 v[212:213], off
	v_lshl_add_u64 v[212:213], v[218:219], 0, s[34:35]
	s_mov_b32 m0, s45
	s_nop 0
	global_load_lds_dwordx4 v[212:213], off
	s_waitcnt vmcnt(8)
	s_waitcnt lgkmcnt(0)
	s_barrier
	s_setprio 1
	s_waitcnt lgkmcnt(0)
	v_mfma_f32_16x16x32_bf16 v[62:65], v[106:109], v[178:181], v[62:65]
	v_mfma_f32_16x16x32_bf16 v[58:61], v[118:121], v[178:181], v[58:61]
	v_mfma_f32_16x16x32_bf16 v[46:49], v[106:109], v[186:189], v[46:49]
	v_mfma_f32_16x16x32_bf16 v[42:45], v[118:121], v[186:189], v[42:45]
	v_mfma_f32_16x16x32_bf16 v[30:33], v[106:109], v[194:197], v[30:33]
	v_mfma_f32_16x16x32_bf16 v[26:29], v[118:121], v[194:197], v[26:29]
	v_mfma_f32_16x16x32_bf16 v[14:17], v[106:109], v[202:205], v[14:17]
	v_mfma_f32_16x16x32_bf16 v[10:13], v[118:121], v[202:205], v[10:13]
	v_mfma_f32_16x16x32_bf16 v[62:65], v[114:117], v[182:185], v[62:65]
	v_mfma_f32_16x16x32_bf16 v[58:61], v[130:133], v[182:185], v[58:61]
	v_mfma_f32_16x16x32_bf16 v[46:49], v[114:117], v[190:193], v[46:49]
	v_mfma_f32_16x16x32_bf16 v[42:45], v[130:133], v[190:193], v[42:45]
	v_mfma_f32_16x16x32_bf16 v[30:33], v[114:117], v[198:201], v[30:33]
	v_mfma_f32_16x16x32_bf16 v[26:29], v[130:133], v[198:201], v[26:29]
	v_mfma_f32_16x16x32_bf16 v[14:17], v[114:117], v[208:211], v[14:17]
	v_mfma_f32_16x16x32_bf16 v[10:13], v[130:133], v[208:211], v[10:13]
	s_setprio 0
	s_setprio 1
	v_mfma_f32_16x16x32_bf16 v[54:57], v[146:149], v[178:181], v[54:57]
	v_mfma_f32_16x16x32_bf16 v[50:53], v[154:157], v[178:181], v[50:53]
	v_mfma_f32_16x16x32_bf16 v[38:41], v[146:149], v[186:189], v[38:41]
	v_mfma_f32_16x16x32_bf16 v[34:37], v[154:157], v[186:189], v[34:37]
	v_mfma_f32_16x16x32_bf16 v[22:25], v[146:149], v[194:197], v[22:25]
	v_mfma_f32_16x16x32_bf16 v[18:21], v[154:157], v[194:197], v[18:21]
	v_mfma_f32_16x16x32_bf16 v[6:9], v[146:149], v[202:205], v[6:9]
	v_mfma_f32_16x16x32_bf16 v[2:5], v[154:157], v[202:205], v[2:5]
	v_mfma_f32_16x16x32_bf16 v[54:57], v[150:153], v[182:185], v[54:57]
	v_mfma_f32_16x16x32_bf16 v[50:53], v[158:161], v[182:185], v[50:53]
	v_mfma_f32_16x16x32_bf16 v[38:41], v[150:153], v[190:193], v[38:41]
	v_mfma_f32_16x16x32_bf16 v[34:37], v[158:161], v[190:193], v[34:37]
	v_mfma_f32_16x16x32_bf16 v[22:25], v[150:153], v[198:201], v[22:25]
	v_mfma_f32_16x16x32_bf16 v[18:21], v[158:161], v[198:201], v[18:21]
	v_mfma_f32_16x16x32_bf16 v[6:9], v[150:153], v[208:211], v[6:9]
	v_mfma_f32_16x16x32_bf16 v[2:5], v[158:161], v[208:211], v[2:5]
	s_setprio 0
	s_add_i32 s52, s52, 2
	s_add_u32 s14, s14, 0x100
	s_addc_u32 s15, s15, 0
	s_add_u32 s50, s50, 0x100
	s_addc_u32 s51, s51, 0
	s_cmp_gt_u32 s52, 13
	s_cbranch_scc1 .Lbe_go_exit
	s_add_u32 s20, s14, 0xfffc0080
	s_addc_u32 s21, s15, -1
	s_add_i32 s53, 0, 0x10000
	s_cmp_eq_u32 s52, 12
	s_cselect_b32 s23, s17, s21
	s_cselect_b32 s22, s19, s20
	s_cselect_b32 s21, s9, s51
	s_cselect_b32 s20, s49, s50
	s_add_i32 s56, 0, 0x14000
	s_branch .LBB0_906
.Lbe_go_exit:
	s_barrier
	s_and_b64 vcc, exec, s[4:5]
	s_cbranch_vccz .LBB0_909
	s_barrier

;     ...
;     const bool has_next = unit(ui + 1, npm, npn, nkq);
;     const char* nA = has_next ? (const char*)A + (size_t)npm * tstep + (nkq > 0 ? (size_t)nkq * (K / 4) * 2 : 0) : cA;
;     const char* nB = has_next ? (const char*)Bt + (size_t)npn * tstep + (nkq > 0 ? (size_t)nkq * (K / 4) * 2 : 0) : cB;
;     const int ntu = (SPLIT && kq >= 0) ? nt / 4 : nt;
;     for (int t = 0; t < ntu; t += 2) {
;       const bool last = (t == ntu - 2);
;       const char* a1 = cA + (size_t)(t + 1) * kstep;
;       const char* a2 = last ? nA : cA + (size_t)(t + 2) * kstep;
;       const char* b2 = last ? nB : cB + (size_t)(t + 2) * kstep;
;     ...
;     for (int a = 0; a < 2; ++a)
; #pragma unroll
;       for (int b = 0; b < 2; ++b)
; #pragma unroll
;         for (int m = 0; m < 4; ++m)
; #pragma unroll
;           for (int n = 0; n < 2; ++n) acc[a][b][m][n] = (f32x4){0.f, 0.f, 0.f, 0.f};
;     pm = npm; pn = npn; kq = nkq; cA = nA; cB = nB; ++ui;
.LBB0_993:
	s_ashr_i32 s11, s10, 31
	s_lshl_b64 s[14:15], s[10:11], 19
	s_add_u32 s14, s76, s14
	s_addc_u32 s15, s77, s15
	s_and_b64 s[16:17], s[0:1], exec
	s_cselect_b32 s11, s15, s21
	s_cselect_b32 s48, s14, s20
	s_ashr_i32 s13, s12, 31
	s_lshl_b64 s[16:17], s[12:13], 19
	s_add_u32 s16, s26, s16
	s_addc_u32 s17, s27, s17
	s_and_b64 s[24:25], s[0:1], exec
	s_cselect_b32 s13, s17, s23
	s_cselect_b32 s49, s16, s22
	s_add_u32 s20, s20, 0x40080
	s_addc_u32 s21, s21, 0
	s_add_u32 s50, s22, 0x100
	v_mov_b32_e32 v2, 0
	s_addc_u32 s51, s23, 0
	s_mov_b32 s52, -2
	v_mov_b32_e32 v3, v2
	v_mov_b32_e32 v4, v2
	v_mov_b32_e32 v5, v2
	v_mov_b32_e32 v6, v2
	v_mov_b32_e32 v7, v2
	v_mov_b32_e32 v8, v2
	v_mov_b32_e32 v9, v2
	v_mov_b32_e32 v18, v2
	v_mov_b32_e32 v19, v2
	v_mov_b32_e32 v20, v2
	v_mov_b32_e32 v21, v2
	v_mov_b32_e32 v22, v2
	v_mov_b32_e32 v23, v2
	v_mov_b32_e32 v24, v2
	v_mov_b32_e32 v25, v2
	v_mov_b32_e32 v34, v2
	v_mov_b32_e32 v35, v2
	v_mov_b32_e32 v36, v2
	v_mov_b32_e32 v37, v2
	v_mov_b32_e32 v38, v2
	v_mov_b32_e32 v39, v2
	v_mov_b32_e32 v40, v2
	v_mov_b32_e32 v41, v2
	v_mov_b32_e32 v50, v2
	v_mov_b32_e32 v51, v2
	v_mov_b32_e32 v52, v2
	v_mov_b32_e32 v53, v2
	v_mov_b32_e32 v54, v2
	v_mov_b32_e32 v55, v2
	v_mov_b32_e32 v56, v2
	v_mov_b32_e32 v57, v2
	v_mov_b32_e32 v10, v2
	v_mov_b32_e32 v11, v2
	v_mov_b32_e32 v12, v2
	v_mov_b32_e32 v13, v2
	v_mov_b32_e32 v14, v2
	v_mov_b32_e32 v15, v2
	v_mov_b32_e32 v16, v2
	v_mov_b32_e32 v17, v2
	v_mov_b32_e32 v26, v2
	v_mov_b32_e32 v27, v2
	v_mov_b32_e32 v28, v2
	v_mov_b32_e32 v29, v2
	v_mov_b32_e32 v30, v2
	v_mov_b32_e32 v31, v2
	v_mov_b32_e32 v32, v2
	v_mov_b32_e32 v33, v2
	v_mov_b32_e32 v42, v2
	v_mov_b32_e32 v43, v2
	v_mov_b32_e32 v44, v2
	v_mov_b32_e32 v45, v2
	v_mov_b32_e32 v46, v2
	v_mov_b32_e32 v47, v2
	v_mov_b32_e32 v48, v2
	v_mov_b32_e32 v49, v2
	v_mov_b32_e32 v58, v2
	v_mov_b32_e32 v59, v2
	v_mov_b32_e32 v60, v2
	v_mov_b32_e32 v61, v2
	v_mov_b32_e32 v62, v2
	v_mov_b32_e32 v63, v2
	v_mov_b32_e32 v64, v2
	v_mov_b32_e32 v65, v2
	v_mov_b32_e32 v66, v2
	v_mov_b32_e32 v67, v2
	v_mov_b32_e32 v68, v2
	v_mov_b32_e32 v69, v2
	v_mov_b32_e32 v70, v2
	v_mov_b32_e32 v71, v2
	v_mov_b32_e32 v72, v2
	v_mov_b32_e32 v73, v2
	v_mov_b32_e32 v82, v2
	v_mov_b32_e32 v83, v2
	v_mov_b32_e32 v84, v2
	v_mov_b32_e32 v85, v2
	v_mov_b32_e32 v86, v2
	v_mov_b32_e32 v87, v2
	v_mov_b32_e32 v88, v2
	v_mov_b32_e32 v89, v2
	v_mov_b32_e32 v98, v2
	v_mov_b32_e32 v99, v2
	v_mov_b32_e32 v100, v2
	v_mov_b32_e32 v101, v2
	v_mov_b32_e32 v102, v2
	s_waitcnt vmcnt(0)
	v_mov_b32_e32 v103, v2
	v_mov_b32_e32 v104, v2
	v_mov_b32_e32 v105, v2
	v_mov_b32_e32 v114, v2
	v_mov_b32_e32 v115, v2
	v_mov_b32_e32 v116, v2
	v_mov_b32_e32 v117, v2
	v_mov_b32_e32 v118, v2
	v_mov_b32_e32 v119, v2
	v_mov_b32_e32 v120, v2
	v_mov_b32_e32 v121, v2
	v_mov_b32_e32 v74, v2
	v_mov_b32_e32 v75, v2
	v_mov_b32_e32 v76, v2
	v_mov_b32_e32 v77, v2
	v_mov_b32_e32 v78, v2
	v_mov_b32_e32 v79, v2
	v_mov_b32_e32 v80, v2
	v_mov_b32_e32 v81, v2
	v_mov_b32_e32 v90, v2
	v_mov_b32_e32 v91, v2
	v_mov_b32_e32 v92, v2
	v_mov_b32_e32 v93, v2
	v_mov_b32_e32 v94, v2
	v_mov_b32_e32 v95, v2
	v_mov_b32_e32 v96, v2
	v_mov_b32_e32 v97, v2
	v_mov_b32_e32 v106, v2
	v_mov_b32_e32 v107, v2
	v_mov_b32_e32 v108, v2
	v_mov_b32_e32 v109, v2
	v_mov_b32_e32 v110, v2
	v_mov_b32_e32 v111, v2
	v_mov_b32_e32 v112, v2
	v_mov_b32_e32 v113, v2
	v_mov_b32_e32 v122, v2
	v_mov_b32_e32 v123, v2
	v_mov_b32_e32 v124, v2
	v_mov_b32_e32 v125, v2
	v_mov_b32_e32 v126, v2
	v_mov_b32_e32 v127, v2
	v_mov_b32_e32 v128, v2
	v_mov_b32_e32 v129, v2
	s_add_u32 s22, s20, 0xfffc0080
	s_addc_u32 s23, s21, -1
	s_add_i32 s53, 0, 0x10000
	s_cmp_eq_u32 s52, 12
	s_cselect_b32 s25, s11, s23
	s_cselect_b32 s24, s48, s22
	s_cselect_b32 s23, s13, s51
	s_cselect_b32 s22, s49, s50
	s_add_i32 s56, 0, 0x14000
	s_branch .Lbe_m1_body

; #define WAIT_V(n) asm volatile("s_waitcnt vmcnt(" #n ")" ::: "memory")
; #define WAIT_L(n) asm volatile("s_waitcnt lgkmcnt(" #n ")" ::: "memory")
; #define BAR __builtin_amdgcn_s_barrier()
; #define SCHED __builtin_amdgcn_sched_barrier(0)
;     ...
;       LDB(B0, 0, 0); LDB(B1, 0, 1); SCHED; LDA(At, 0, 0); STAGE(SAo(1, 1), a1 + hstep, voff);
;       WAIT_V(8); WAIT_L(0); BAR; MMA(0, 0, At, B0); MMA(0, 1, At, B1); BAR; SCHED;
;       LDA(At, 0, 1); STAGE(SBo(0, 0), b2, voffB); STAGE(SBo(0, 1), b2 + hstep, voffB); STAGE(SAo(0, 0), a2, voff);
;       WAIT_V(8); WAIT_L(0); BAR; MMA(1, 0, At, B0); MMA(1, 1, At, B1); BAR; SCHED;
.Lbe_m1_body:
	v_add_u32_e32 v142, s53, v158
	v_add_u32_e32 v156, s56, v158
	ds_read_b128 v[130:133], v142
	ds_read_b128 v[134:137], v142 offset:1024
	ds_read_b128 v[138:141], v142 offset:2048
	ds_read_b128 v[142:145], v142 offset:3072
	ds_read_b128 v[160:163], v156
	ds_read_b128 v[164:167], v156 offset:1024
	ds_read_b128 v[168:171], v156 offset:2048
	ds_read_b128 v[178:181], v156 offset:3072
	v_lshl_add_u64 v[156:157], s[20:21], 0, v[152:153]
	s_add_i32 m0, s19, 0xc000
	ds_read_b128 v[182:185], v159
	ds_read_b128 v[186:189], v159 offset:1024
	ds_read_b128 v[190:193], v159 offset:2048
	ds_read_b128 v[194:197], v159 offset:3072
	ds_read_b128 v[198:201], v159 offset:4096
	ds_read_b128 v[202:205], v159 offset:5120
	ds_read_b128 v[206:209], v159 offset:6144
	ds_read_b128 v[210:213], v159 offset:7168
	global_load_lds_dwordx4 v[156:157], off
	v_lshl_add_u64 v[156:157], s[20:21], 0, v[154:155]
	s_add_i32 m0, s19, 0xe000
	s_nop 0
	global_load_lds_dwordx4 v[156:157], off
	s_waitcnt vmcnt(8)
	s_waitcnt lgkmcnt(0)
	s_barrier
	s_setprio 1
	s_waitcnt lgkmcnt(0)
	v_mfma_f32_16x16x32_bf16 v[126:129], v[130:133], v[182:185], v[126:129]
	v_mfma_f32_16x16x32_bf16 v[122:125], v[138:141], v[182:185], v[122:125]
	v_mfma_f32_16x16x32_bf16 v[110:113], v[130:133], v[190:193], v[110:113]
	v_mfma_f32_16x16x32_bf16 v[106:109], v[138:141], v[190:193], v[106:109]
	v_mfma_f32_16x16x32_bf16 v[94:97], v[130:133], v[198:201], v[94:97]
	v_mfma_f32_16x16x32_bf16 v[90:93], v[138:141], v[198:201], v[90:93]
	v_mfma_f32_16x16x32_bf16 v[78:81], v[130:133], v[206:209], v[78:81]
	v_mfma_f32_16x16x32_bf16 v[74:77], v[138:141], v[206:209], v[74:77]
	v_mfma_f32_16x16x32_bf16 v[126:129], v[134:137], v[186:189], v[126:129]
	v_mfma_f32_16x16x32_bf16 v[122:125], v[142:145], v[186:189], v[122:125]
	v_mfma_f32_16x16x32_bf16 v[110:113], v[134:137], v[194:197], v[110:113]
	v_mfma_f32_16x16x32_bf16 v[106:109], v[142:145], v[194:197], v[106:109]
	v_mfma_f32_16x16x32_bf16 v[94:97], v[134:137], v[202:205], v[94:97]
	v_mfma_f32_16x16x32_bf16 v[90:93], v[142:145], v[202:205], v[90:93]
	v_mfma_f32_16x16x32_bf16 v[78:81], v[134:137], v[210:213], v[78:81]
	v_mfma_f32_16x16x32_bf16 v[74:77], v[142:145], v[210:213], v[74:77]
	s_setprio 0
	s_setprio 1
	v_mfma_f32_16x16x32_bf16 v[118:121], v[160:163], v[182:185], v[118:121]
	v_mfma_f32_16x16x32_bf16 v[114:117], v[168:171], v[182:185], v[114:117]
	v_mfma_f32_16x16x32_bf16 v[102:105], v[160:163], v[190:193], v[102:105]
	v_mfma_f32_16x16x32_bf16 v[98:101], v[168:171], v[190:193], v[98:101]
	v_mfma_f32_16x16x32_bf16 v[86:89], v[160:163], v[198:201], v[86:89]
	v_mfma_f32_16x16x32_bf16 v[82:85], v[168:171], v[198:201], v[82:85]
	v_mfma_f32_16x16x32_bf16 v[70:73], v[160:163], v[206:209], v[70:73]
	v_mfma_f32_16x16x32_bf16 v[66:69], v[168:171], v[206:209], v[66:69]
	v_mfma_f32_16x16x32_bf16 v[118:121], v[164:167], v[186:189], v[118:121]
	v_mfma_f32_16x16x32_bf16 v[114:117], v[178:181], v[186:189], v[114:117]
	v_mfma_f32_16x16x32_bf16 v[102:105], v[164:167], v[194:197], v[102:105]
	v_mfma_f32_16x16x32_bf16 v[98:101], v[178:181], v[194:197], v[98:101]
	v_mfma_f32_16x16x32_bf16 v[86:89], v[164:167], v[202:205], v[86:89]
	v_mfma_f32_16x16x32_bf16 v[82:85], v[178:181], v[202:205], v[82:85]
	v_mfma_f32_16x16x32_bf16 v[70:73], v[164:167], v[210:213], v[70:73]
	v_mfma_f32_16x16x32_bf16 v[66:69], v[178:181], v[210:213], v[66:69]
	s_setprio 0
	s_barrier
	s_add_i32 s53, s53, s29
	v_lshl_add_u64 v[156:157], s[22:23], 0, v[0:1]
	s_mov_b32 m0, s53
	ds_read_b128 v[182:185], v159 offset:16384
	ds_read_b128 v[186:189], v159 offset:17408
	ds_read_b128 v[190:193], v159 offset:18432
	ds_read_b128 v[194:197], v159 offset:19456
	ds_read_b128 v[198:201], v159 offset:20480
	ds_read_b128 v[202:205], v159 offset:21504
	ds_read_b128 v[206:209], v159 offset:22528
	ds_read_b128 v[210:213], v159 offset:23552
	global_load_lds_dwordx4 v[156:157], off
	s_add_i32 m0, s53, 0x2000
	s_add_u32 s54, s22, 0x40000
	v_lshl_add_u64 v[214:215], s[22:23], 0, v[146:147]
	s_addc_u32 s55, s23, 0
	s_add_i32 s53, s56, s29
	global_load_lds_dwordx4 v[214:215], off
	v_lshl_add_u64 v[216:217], s[54:55], 0, v[0:1]
	s_mov_b32 m0, s53
	v_lshl_add_u64 v[218:219], s[24:25], 0, v[148:149]
	global_load_lds_dwordx4 v[216:217], off
	v_lshl_add_u64 v[216:217], s[54:55], 0, v[146:147]
	s_add_i32 m0, s53, 0x2000
	s_nop 0
	global_load_lds_dwordx4 v[216:217], off
	v_lshl_add_u64 v[216:217], s[24:25], 0, v[150:151]
	s_mov_b32 m0, s19
	s_nop 0
	global_load_lds_dwordx4 v[216:217], off
	s_mov_b32 m0, s30
	s_nop 0
	global_load_lds_dwordx4 v[218:219], off
	s_waitcnt vmcnt(8)
	s_waitcnt lgkmcnt(0)
	s_barrier
; #define WAIT_V(n) asm volatile("s_waitcnt vmcnt(" #n ")" ::: "memory")
; #define WAIT_L(n) asm volatile("s_waitcnt lgkmcnt(" #n ")" ::: "memory")
; #define BAR __builtin_amdgcn_s_barrier()
; #define SCHED __builtin_amdgcn_sched_barrier(0)
;     ...
;       WAIT_V(8); WAIT_L(0); BAR; MMA(1, 0, At, B0); MMA(1, 1, At, B1); BAR; SCHED;
;       LDB(B0, 1, 0); LDB(B1, 1, 1); SCHED; LDA(At, 1, 0); STAGE(SAo(0, 1), a2 + hstep, voff);
;       WAIT_V(8); WAIT_L(0); BAR; MMA(0, 0, At, B0); MMA(0, 1, At, B1); BAR; SCHED;
	s_setprio 1
	s_waitcnt lgkmcnt(0)
	v_mfma_f32_16x16x32_bf16 v[62:65], v[130:133], v[182:185], v[62:65]
	v_mfma_f32_16x16x32_bf16 v[58:61], v[138:141], v[182:185], v[58:61]
	v_mfma_f32_16x16x32_bf16 v[46:49], v[130:133], v[190:193], v[46:49]
	v_mfma_f32_16x16x32_bf16 v[42:45], v[138:141], v[190:193], v[42:45]
	v_mfma_f32_16x16x32_bf16 v[30:33], v[130:133], v[198:201], v[30:33]
	v_mfma_f32_16x16x32_bf16 v[26:29], v[138:141], v[198:201], v[26:29]
	v_mfma_f32_16x16x32_bf16 v[14:17], v[130:133], v[206:209], v[14:17]
	v_mfma_f32_16x16x32_bf16 v[10:13], v[138:141], v[206:209], v[10:13]
	v_mfma_f32_16x16x32_bf16 v[62:65], v[134:137], v[186:189], v[62:65]
	v_mfma_f32_16x16x32_bf16 v[58:61], v[142:145], v[186:189], v[58:61]
	v_mfma_f32_16x16x32_bf16 v[46:49], v[134:137], v[194:197], v[46:49]
	v_mfma_f32_16x16x32_bf16 v[42:45], v[142:145], v[194:197], v[42:45]
	v_mfma_f32_16x16x32_bf16 v[30:33], v[134:137], v[202:205], v[30:33]
	v_mfma_f32_16x16x32_bf16 v[26:29], v[142:145], v[202:205], v[26:29]
	v_mfma_f32_16x16x32_bf16 v[14:17], v[134:137], v[210:213], v[14:17]
	v_mfma_f32_16x16x32_bf16 v[10:13], v[142:145], v[210:213], v[10:13]
	s_setprio 0
	s_setprio 1
	v_mfma_f32_16x16x32_bf16 v[54:57], v[160:163], v[182:185], v[54:57]
	v_mfma_f32_16x16x32_bf16 v[50:53], v[168:171], v[182:185], v[50:53]
	v_mfma_f32_16x16x32_bf16 v[38:41], v[160:163], v[190:193], v[38:41]
	v_mfma_f32_16x16x32_bf16 v[34:37], v[168:171], v[190:193], v[34:37]
	v_mfma_f32_16x16x32_bf16 v[22:25], v[160:163], v[198:201], v[22:25]
	v_mfma_f32_16x16x32_bf16 v[18:21], v[168:171], v[198:201], v[18:21]
	v_mfma_f32_16x16x32_bf16 v[6:9], v[160:163], v[206:209], v[6:9]
	v_mfma_f32_16x16x32_bf16 v[2:5], v[168:171], v[206:209], v[2:5]
	v_mfma_f32_16x16x32_bf16 v[54:57], v[164:167], v[186:189], v[54:57]
	v_mfma_f32_16x16x32_bf16 v[50:53], v[178:181], v[186:189], v[50:53]
	v_mfma_f32_16x16x32_bf16 v[38:41], v[164:167], v[194:197], v[38:41]
	v_mfma_f32_16x16x32_bf16 v[34:37], v[178:181], v[194:197], v[34:37]
	v_mfma_f32_16x16x32_bf16 v[22:25], v[164:167], v[202:205], v[22:25]
	v_mfma_f32_16x16x32_bf16 v[18:21], v[178:181], v[202:205], v[18:21]
	v_mfma_f32_16x16x32_bf16 v[6:9], v[164:167], v[210:213], v[6:9]
	v_mfma_f32_16x16x32_bf16 v[2:5], v[178:181], v[210:213], v[2:5]
	s_setprio 0
	s_barrier
	s_add_i32 s53, 0, 0x18000
	s_add_i32 s54, 0, 0x1c000
	v_add_u32_e32 v142, s53, v158
	v_add_u32_e32 v178, s54, v158
	ds_read_b128 v[130:133], v142
	ds_read_b128 v[134:137], v142 offset:1024
	ds_read_b128 v[138:141], v142 offset:2048
	ds_read_b128 v[142:145], v142 offset:3072
	ds_read_b128 v[160:163], v178
	ds_read_b128 v[164:167], v178 offset:1024
	ds_read_b128 v[168:171], v178 offset:2048
	ds_read_b128 v[178:181], v178 offset:3072
	s_add_u32 s24, s24, 0x40000
	s_addc_u32 s25, s25, 0
	s_mov_b32 m0, s31
	v_lshl_add_u64 v[220:221], s[24:25], 0, v[150:151]
	ds_read_b128 v[182:185], v159 offset:32768
	ds_read_b128 v[186:189], v159 offset:33792
	ds_read_b128 v[190:193], v159 offset:34816
	ds_read_b128 v[194:197], v159 offset:35840
	ds_read_b128 v[198:201], v159 offset:36864
	ds_read_b128 v[202:205], v159 offset:37888
	ds_read_b128 v[206:209], v159 offset:38912
	ds_read_b128 v[210:213], v159 offset:39936
	global_load_lds_dwordx4 v[220:221], off
	v_lshl_add_u64 v[220:221], s[24:25], 0, v[148:149]
	s_mov_b32 m0, s33
	s_nop 0
	global_load_lds_dwordx4 v[220:221], off
	s_waitcnt vmcnt(8)
	s_waitcnt lgkmcnt(0)
	s_barrier
	s_setprio 1
	s_waitcnt lgkmcnt(0)
	v_mfma_f32_16x16x32_bf16 v[126:129], v[130:133], v[182:185], v[126:129]
	v_mfma_f32_16x16x32_bf16 v[122:125], v[138:141], v[182:185], v[122:125]
	v_mfma_f32_16x16x32_bf16 v[110:113], v[130:133], v[190:193], v[110:113]
	v_mfma_f32_16x16x32_bf16 v[106:109], v[138:141], v[190:193], v[106:109]
	v_mfma_f32_16x16x32_bf16 v[94:97], v[130:133], v[198:201], v[94:97]
	v_mfma_f32_16x16x32_bf16 v[90:93], v[138:141], v[198:201], v[90:93]
	v_mfma_f32_16x16x32_bf16 v[78:81], v[130:133], v[206:209], v[78:81]
	v_mfma_f32_16x16x32_bf16 v[74:77], v[138:141], v[206:209], v[74:77]
	v_mfma_f32_16x16x32_bf16 v[126:129], v[134:137], v[186:189], v[126:129]
	v_mfma_f32_16x16x32_bf16 v[122:125], v[142:145], v[186:189], v[122:125]
	v_mfma_f32_16x16x32_bf16 v[110:113], v[134:137], v[194:197], v[110:113]
	v_mfma_f32_16x16x32_bf16 v[106:109], v[142:145], v[194:197], v[106:109]
	v_mfma_f32_16x16x32_bf16 v[94:97], v[134:137], v[202:205], v[94:97]
	v_mfma_f32_16x16x32_bf16 v[90:93], v[142:145], v[202:205], v[90:93]
	v_mfma_f32_16x16x32_bf16 v[78:81], v[134:137], v[210:213], v[78:81]
	v_mfma_f32_16x16x32_bf16 v[74:77], v[142:145], v[210:213], v[74:77]
	s_setprio 0
	s_setprio 1
	v_mfma_f32_16x16x32_bf16 v[118:121], v[160:163], v[182:185], v[118:121]
	v_mfma_f32_16x16x32_bf16 v[114:117], v[168:171], v[182:185], v[114:117]
	v_mfma_f32_16x16x32_bf16 v[102:105], v[160:163], v[190:193], v[102:105]
	v_mfma_f32_16x16x32_bf16 v[98:101], v[168:171], v[190:193], v[98:101]
	v_mfma_f32_16x16x32_bf16 v[86:89], v[160:163], v[198:201], v[86:89]
	v_mfma_f32_16x16x32_bf16 v[82:85], v[168:171], v[198:201], v[82:85]
	v_mfma_f32_16x16x32_bf16 v[70:73], v[160:163], v[206:209], v[70:73]
	v_mfma_f32_16x16x32_bf16 v[66:69], v[168:171], v[206:209], v[66:69]
	v_mfma_f32_16x16x32_bf16 v[118:121], v[164:167], v[186:189], v[118:121]
	v_mfma_f32_16x16x32_bf16 v[114:117], v[178:181], v[186:189], v[114:117]
	v_mfma_f32_16x16x32_bf16 v[102:105], v[164:167], v[194:197], v[102:105]
	v_mfma_f32_16x16x32_bf16 v[98:101], v[178:181], v[194:197], v[98:101]
	v_mfma_f32_16x16x32_bf16 v[86:89], v[164:167], v[202:205], v[86:89]
	v_mfma_f32_16x16x32_bf16 v[82:85], v[178:181], v[202:205], v[82:85]
	v_mfma_f32_16x16x32_bf16 v[70:73], v[164:167], v[210:213], v[70:73]
	v_mfma_f32_16x16x32_bf16 v[66:69], v[178:181], v[210:213], v[66:69]
	s_setprio 0
	s_barrier
; #define WAIT_V(n) asm volatile("s_waitcnt vmcnt(" #n ")" ::: "memory")
; #define WAIT_L(n) asm volatile("s_waitcnt lgkmcnt(" #n ")" ::: "memory")
; #define BAR __builtin_amdgcn_s_barrier()
; #define SCHED __builtin_amdgcn_sched_barrier(0)
;     ...
;       LDA(At, 1, 1); STAGE(SBo(1, 0), b3, voffB); STAGE(SBo(1, 1), b3 + hstep, voffB); STAGE(SAo(1, 0), a3, voff);
;       WAIT_V(8); WAIT_L(0); BAR; MMA(1, 0, At, B0); MMA(1, 1, At, B1); BAR; SCHED;
;     }
;     if (wr == 0) BAR;
	s_add_i32 s24, s53, s29
	v_lshl_add_u64 v[156:157], v[156:157], 0, s[34:35]
	s_mov_b32 m0, s24
	ds_read_b128 v[182:185], v159 offset:49152
	ds_read_b128 v[186:189], v159 offset:50176
	ds_read_b128 v[190:193], v159 offset:51200
	ds_read_b128 v[194:197], v159 offset:52224
	ds_read_b128 v[198:201], v159 offset:53248
	ds_read_b128 v[202:205], v159 offset:54272
	ds_read_b128 v[206:209], v159 offset:55296
	ds_read_b128 v[210:213], v159 offset:56320
	global_load_lds_dwordx4 v[156:157], off
	s_add_i32 m0, s24, 0x2000
	s_add_u32 s22, s22, 0x40080
	v_lshl_add_u64 v[156:157], v[214:215], 0, s[34:35]
	s_addc_u32 s23, s23, 0
	s_add_i32 s24, s54, s29
	global_load_lds_dwordx4 v[156:157], off
	v_lshl_add_u64 v[156:157], s[22:23], 0, v[0:1]
	s_mov_b32 m0, s24
	s_nop 0
	global_load_lds_dwordx4 v[156:157], off
	v_lshl_add_u64 v[156:157], s[22:23], 0, v[146:147]
	s_add_i32 m0, s24, 0x2000
	s_nop 0
	global_load_lds_dwordx4 v[156:157], off
	v_lshl_add_u64 v[156:157], v[216:217], 0, s[34:35]
	s_mov_b32 m0, s42
	s_nop 0
	global_load_lds_dwordx4 v[156:157], off
	v_lshl_add_u64 v[156:157], v[218:219], 0, s[34:35]
	s_mov_b32 m0, s43
	s_nop 0
	global_load_lds_dwordx4 v[156:157], off
	s_waitcnt vmcnt(8)
	s_waitcnt lgkmcnt(0)
	s_barrier
	s_setprio 1
	s_waitcnt lgkmcnt(0)
	v_mfma_f32_16x16x32_bf16 v[62:65], v[130:133], v[182:185], v[62:65]
	v_mfma_f32_16x16x32_bf16 v[58:61], v[138:141], v[182:185], v[58:61]
	v_mfma_f32_16x16x32_bf16 v[46:49], v[130:133], v[190:193], v[46:49]
	v_mfma_f32_16x16x32_bf16 v[42:45], v[138:141], v[190:193], v[42:45]
	v_mfma_f32_16x16x32_bf16 v[30:33], v[130:133], v[198:201], v[30:33]
	v_mfma_f32_16x16x32_bf16 v[26:29], v[138:141], v[198:201], v[26:29]
	v_mfma_f32_16x16x32_bf16 v[14:17], v[130:133], v[206:209], v[14:17]
	v_mfma_f32_16x16x32_bf16 v[10:13], v[138:141], v[206:209], v[10:13]
	v_mfma_f32_16x16x32_bf16 v[62:65], v[134:137], v[186:189], v[62:65]
	v_mfma_f32_16x16x32_bf16 v[58:61], v[142:145], v[186:189], v[58:61]
	v_mfma_f32_16x16x32_bf16 v[46:49], v[134:137], v[194:197], v[46:49]
	v_mfma_f32_16x16x32_bf16 v[42:45], v[142:145], v[194:197], v[42:45]
	v_mfma_f32_16x16x32_bf16 v[30:33], v[134:137], v[202:205], v[30:33]
	v_mfma_f32_16x16x32_bf16 v[26:29], v[142:145], v[202:205], v[26:29]
	v_mfma_f32_16x16x32_bf16 v[14:17], v[134:137], v[210:213], v[14:17]
	v_mfma_f32_16x16x32_bf16 v[10:13], v[142:145], v[210:213], v[10:13]
	s_setprio 0
	s_setprio 1
	v_mfma_f32_16x16x32_bf16 v[54:57], v[160:163], v[182:185], v[54:57]
	v_mfma_f32_16x16x32_bf16 v[50:53], v[168:171], v[182:185], v[50:53]
	v_mfma_f32_16x16x32_bf16 v[38:41], v[160:163], v[190:193], v[38:41]
	v_mfma_f32_16x16x32_bf16 v[34:37], v[168:171], v[190:193], v[34:37]
	v_mfma_f32_16x16x32_bf16 v[22:25], v[160:163], v[198:201], v[22:25]
	v_mfma_f32_16x16x32_bf16 v[18:21], v[168:171], v[198:201], v[18:21]
	v_mfma_f32_16x16x32_bf16 v[6:9], v[160:163], v[206:209], v[6:9]
	v_mfma_f32_16x16x32_bf16 v[2:5], v[168:171], v[206:209], v[2:5]
	v_mfma_f32_16x16x32_bf16 v[54:57], v[164:167], v[186:189], v[54:57]
	v_mfma_f32_16x16x32_bf16 v[50:53], v[178:181], v[186:189], v[50:53]
	v_mfma_f32_16x16x32_bf16 v[38:41], v[164:167], v[194:197], v[38:41]
	v_mfma_f32_16x16x32_bf16 v[34:37], v[178:181], v[194:197], v[34:37]
	v_mfma_f32_16x16x32_bf16 v[22:25], v[164:167], v[202:205], v[22:25]
	v_mfma_f32_16x16x32_bf16 v[18:21], v[178:181], v[202:205], v[18:21]
	v_mfma_f32_16x16x32_bf16 v[6:9], v[164:167], v[210:213], v[6:9]
	v_mfma_f32_16x16x32_bf16 v[2:5], v[178:181], v[210:213], v[2:5]
	s_setprio 0
	s_add_i32 s52, s52, 2
	s_add_u32 s20, s20, 0x100
	s_addc_u32 s21, s21, 0
	s_add_u32 s50, s50, 0x100
	s_addc_u32 s51, s51, 0
	s_cmp_gt_u32 s52, 13
	s_cbranch_scc1 .Lbe_m1_exit
	s_add_u32 s22, s20, 0xfffc0080
	s_addc_u32 s23, s21, -1
	s_add_i32 s53, 0, 0x10000
	s_cmp_eq_u32 s52, 12
	s_cselect_b32 s25, s11, s23
	s_cselect_b32 s24, s48, s22
	s_cselect_b32 s23, s13, s51
	s_cselect_b32 s22, s49, s50
	s_add_i32 s56, 0, 0x14000
	s_branch .LBB0_994
.Lbe_m1_exit:
	s_barrier
	s_and_b64 vcc, exec, s[8:9]
	s_cbranch_vccz .LBB0_997
	s_barrier

;     ...
;     const bool has_next = unit(ui + 1, npm, npn, nkq);
;     const char* nA = has_next ? (const char*)A + (size_t)npm * tstep + (nkq > 0 ? (size_t)nkq * (K / 4) * 2 : 0) : cA;
;     const char* nB = has_next ? (const char*)Bt + (size_t)npn * tstep + (nkq > 0 ? (size_t)nkq * (K / 4) * 2 : 0) : cB;
;     const int ntu = (SPLIT && kq >= 0) ? nt / 4 : nt;
;     for (int t = 0; t < ntu; t += 2) {
;       const bool last = (t == ntu - 2);
;       const char* a1 = cA + (size_t)(t + 1) * kstep;
;       const char* a2 = last ? nA : cA + (size_t)(t + 2) * kstep;
;       const char* b2 = last ? nB : cB + (size_t)(t + 2) * kstep;
;     ...
;     for (int a = 0; a < 2; ++a)
; #pragma unroll
;       for (int b = 0; b < 2; ++b)
; #pragma unroll
;         for (int m = 0; m < 4; ++m)
; #pragma unroll
;           for (int n = 0; n < 2; ++n) acc[a][b][m][n] = (f32x4){0.f, 0.f, 0.f, 0.f};
;     pm = npm; pn = npn; kq = nkq; cA = nA; cB = nB; ++ui;
.LBB0_1063:
	v_readlane_b32 s8, v254, 34
	v_readlane_b32 s9, v254, 35
	s_mov_b32 s7, s9
	s_lshl_b64 s[8:9], s[6:7], 21
	s_add_u32 s8, s84, s8
	s_addc_u32 s9, s85, s9
	s_and_b64 s[10:11], s[0:1], exec
	s_cselect_b32 s7, s9, s13
	s_cselect_b32 s42, s8, s12
	s_lshl_b32 s10, s31, 21
	s_add_u32 s10, s24, s10
	s_addc_u32 s11, s25, 0
	s_and_b64 s[16:17], s[0:1], exec
	s_cselect_b32 s43, s11, s15
	s_cselect_b32 s44, s10, s14
	s_add_u32 s12, s12, 0x100080
	s_addc_u32 s13, s13, 0
	s_add_u32 s45, s14, 0x100
	v_mov_b32_e32 v2, 0
	s_addc_u32 s46, s15, 0
	s_mov_b32 s47, -2
	v_mov_b32_e32 v3, v2
	v_mov_b32_e32 v4, v2
	v_mov_b32_e32 v5, v2
	v_mov_b32_e32 v6, v2
	v_mov_b32_e32 v7, v2
	v_mov_b32_e32 v8, v2
	v_mov_b32_e32 v9, v2
	v_mov_b32_e32 v10, v2
	v_mov_b32_e32 v11, v2
	v_mov_b32_e32 v12, v2
	v_mov_b32_e32 v13, v2
	v_mov_b32_e32 v18, v2
	v_mov_b32_e32 v19, v2
	v_mov_b32_e32 v20, v2
	v_mov_b32_e32 v21, v2
	v_mov_b32_e32 v30, v2
	v_mov_b32_e32 v31, v2
	v_mov_b32_e32 v32, v2
	v_mov_b32_e32 v33, v2
	v_mov_b32_e32 v38, v2
	v_mov_b32_e32 v39, v2
	v_mov_b32_e32 v40, v2
	v_mov_b32_e32 v41, v2
	v_mov_b32_e32 v42, v2
	v_mov_b32_e32 v43, v2
	v_mov_b32_e32 v44, v2
	v_mov_b32_e32 v45, v2
	v_mov_b32_e32 v50, v2
	v_mov_b32_e32 v51, v2
	v_mov_b32_e32 v52, v2
	v_mov_b32_e32 v53, v2
	v_mov_b32_e32 v14, v2
	v_mov_b32_e32 v15, v2
	v_mov_b32_e32 v16, v2
	v_mov_b32_e32 v17, v2
	v_mov_b32_e32 v22, v2
	v_mov_b32_e32 v23, v2
	v_mov_b32_e32 v24, v2
	v_mov_b32_e32 v25, v2
	v_mov_b32_e32 v26, v2
	v_mov_b32_e32 v27, v2
	v_mov_b32_e32 v28, v2
	v_mov_b32_e32 v29, v2
	v_mov_b32_e32 v34, v2
	v_mov_b32_e32 v35, v2
	v_mov_b32_e32 v36, v2
	v_mov_b32_e32 v37, v2
	v_mov_b32_e32 v46, v2
	v_mov_b32_e32 v47, v2
	v_mov_b32_e32 v48, v2
	v_mov_b32_e32 v49, v2
	v_mov_b32_e32 v54, v2
	v_mov_b32_e32 v55, v2
	v_mov_b32_e32 v56, v2
	v_mov_b32_e32 v57, v2
	v_mov_b32_e32 v58, v2
	v_mov_b32_e32 v59, v2
	v_mov_b32_e32 v60, v2
	v_mov_b32_e32 v61, v2
	v_mov_b32_e32 v62, v2
	v_mov_b32_e32 v63, v2
	v_mov_b32_e32 v64, v2
	v_mov_b32_e32 v65, v2
	v_mov_b32_e32 v66, v2
	v_mov_b32_e32 v67, v2
	v_mov_b32_e32 v68, v2
	v_mov_b32_e32 v69, v2
	v_mov_b32_e32 v70, v2
	v_mov_b32_e32 v71, v2
	v_mov_b32_e32 v72, v2
	v_mov_b32_e32 v73, v2
	v_mov_b32_e32 v74, v2
	v_mov_b32_e32 v75, v2
	v_mov_b32_e32 v76, v2
	v_mov_b32_e32 v77, v2
	v_mov_b32_e32 v82, v2
	v_mov_b32_e32 v83, v2
	v_mov_b32_e32 v84, v2
	v_mov_b32_e32 v85, v2
	v_mov_b32_e32 v98, v2
	v_mov_b32_e32 v99, v2
	v_mov_b32_e32 v100, v2
	v_mov_b32_e32 v101, v2
	v_mov_b32_e32 v102, v2
	s_waitcnt vmcnt(0)
	v_mov_b32_e32 v103, v2
	v_mov_b32_e32 v104, v2
	v_mov_b32_e32 v105, v2
	v_mov_b32_e32 v106, v2
	v_mov_b32_e32 v107, v2
	v_mov_b32_e32 v108, v2
	v_mov_b32_e32 v109, v2
	v_mov_b32_e32 v118, v2
	v_mov_b32_e32 v119, v2
	v_mov_b32_e32 v120, v2
	v_mov_b32_e32 v121, v2
	v_mov_b32_e32 v78, v2
	v_mov_b32_e32 v79, v2
	v_mov_b32_e32 v80, v2
	v_mov_b32_e32 v81, v2
	v_mov_b32_e32 v86, v2
	v_mov_b32_e32 v87, v2
	v_mov_b32_e32 v88, v2
	v_mov_b32_e32 v89, v2
	v_mov_b32_e32 v90, v2
	v_mov_b32_e32 v91, v2
	v_mov_b32_e32 v92, v2
	v_mov_b32_e32 v93, v2
	v_mov_b32_e32 v94, v2
	v_mov_b32_e32 v95, v2
	v_mov_b32_e32 v96, v2
	v_mov_b32_e32 v97, v2
	v_mov_b32_e32 v110, v2
	v_mov_b32_e32 v111, v2
	v_mov_b32_e32 v112, v2
	v_mov_b32_e32 v113, v2
	v_mov_b32_e32 v114, v2
	v_mov_b32_e32 v115, v2
	v_mov_b32_e32 v116, v2
	v_mov_b32_e32 v117, v2
	v_mov_b32_e32 v122, v2
	v_mov_b32_e32 v123, v2
	v_mov_b32_e32 v124, v2
	v_mov_b32_e32 v125, v2
	v_mov_b32_e32 v126, v2
	v_mov_b32_e32 v127, v2
	v_mov_b32_e32 v128, v2
	v_mov_b32_e32 v129, v2
	s_add_u32 s14, s12, 0xfff00080
	s_addc_u32 s15, s13, -1
	s_add_i32 s48, 0, 0x10000
	s_cmp_eq_u32 s47, 60
	s_cselect_b32 s17, s7, s15
	s_cselect_b32 s16, s42, s14
	s_cselect_b32 s15, s43, s46
	s_cselect_b32 s14, s44, s45
	s_add_i32 s50, 0, 0x14000
	s_branch .Lbe_m2_body

; #define WAIT_V(n) asm volatile("s_waitcnt vmcnt(" #n ")" ::: "memory")
; #define WAIT_L(n) asm volatile("s_waitcnt lgkmcnt(" #n ")" ::: "memory")
; #define BAR __builtin_amdgcn_s_barrier()
; #define SCHED __builtin_amdgcn_sched_barrier(0)
;     ...
;       LDB(B0, 0, 0); LDB(B1, 0, 1); SCHED; LDA(At, 0, 0); STAGE(SAo(1, 1), a1 + hstep, voff);
;       WAIT_V(8); WAIT_L(0); BAR; MMA(0, 0, At, B0); MMA(0, 1, At, B1); BAR; SCHED;
;       LDA(At, 0, 1); STAGE(SBo(0, 0), b2, voffB); STAGE(SBo(0, 1), b2 + hstep, voffB); STAGE(SAo(0, 0), a2, voff);
;       WAIT_V(8); WAIT_L(0); BAR; MMA(1, 0, At, B0); MMA(1, 1, At, B1); BAR; SCHED;
.Lbe_m2_body:
	v_add_u32_e32 v142, s48, v162
	v_add_u32_e32 v160, s50, v162
	ds_read_b128 v[130:133], v142
	ds_read_b128 v[134:137], v142 offset:1024
	ds_read_b128 v[138:141], v142 offset:2048
	ds_read_b128 v[142:145], v142 offset:3072
	ds_read_b128 v[156:159], v160
	ds_read_b128 v[164:167], v160 offset:1024
	ds_read_b128 v[168:171], v160 offset:2048
	ds_read_b128 v[178:181], v160 offset:3072
	v_lshl_add_u64 v[160:161], s[12:13], 0, v[152:153]
	s_add_i32 m0, s19, 0xc000
	ds_read_b128 v[182:185], v163
	ds_read_b128 v[186:189], v163 offset:1024
	ds_read_b128 v[190:193], v163 offset:2048
	ds_read_b128 v[194:197], v163 offset:3072
	ds_read_b128 v[198:201], v163 offset:4096
	ds_read_b128 v[202:205], v163 offset:5120
	ds_read_b128 v[206:209], v163 offset:6144
	ds_read_b128 v[210:213], v163 offset:7168
	global_load_lds_dwordx4 v[160:161], off
	v_lshl_add_u64 v[160:161], s[12:13], 0, v[154:155]
	s_add_i32 m0, s19, 0xe000
	s_nop 0
	global_load_lds_dwordx4 v[160:161], off
	s_waitcnt vmcnt(8)
	s_waitcnt lgkmcnt(0)
	s_barrier
	s_setprio 1
	s_waitcnt lgkmcnt(0)
	v_mfma_f32_16x16x32_bf16 v[126:129], v[130:133], v[182:185], v[126:129]
	v_mfma_f32_16x16x32_bf16 v[122:125], v[138:141], v[182:185], v[122:125]
	v_mfma_f32_16x16x32_bf16 v[114:117], v[130:133], v[190:193], v[114:117]
	v_mfma_f32_16x16x32_bf16 v[110:113], v[138:141], v[190:193], v[110:113]
	v_mfma_f32_16x16x32_bf16 v[94:97], v[130:133], v[198:201], v[94:97]
	v_mfma_f32_16x16x32_bf16 v[90:93], v[138:141], v[198:201], v[90:93]
	v_mfma_f32_16x16x32_bf16 v[86:89], v[130:133], v[206:209], v[86:89]
	v_mfma_f32_16x16x32_bf16 v[78:81], v[138:141], v[206:209], v[78:81]
	v_mfma_f32_16x16x32_bf16 v[126:129], v[134:137], v[186:189], v[126:129]
	v_mfma_f32_16x16x32_bf16 v[122:125], v[142:145], v[186:189], v[122:125]
	v_mfma_f32_16x16x32_bf16 v[114:117], v[134:137], v[194:197], v[114:117]
	v_mfma_f32_16x16x32_bf16 v[110:113], v[142:145], v[194:197], v[110:113]
	v_mfma_f32_16x16x32_bf16 v[94:97], v[134:137], v[202:205], v[94:97]
	v_mfma_f32_16x16x32_bf16 v[90:93], v[142:145], v[202:205], v[90:93]
	v_mfma_f32_16x16x32_bf16 v[86:89], v[134:137], v[210:213], v[86:89]
	v_mfma_f32_16x16x32_bf16 v[78:81], v[142:145], v[210:213], v[78:81]
	s_setprio 0
	s_setprio 1
	v_mfma_f32_16x16x32_bf16 v[118:121], v[156:159], v[182:185], v[118:121]
	v_mfma_f32_16x16x32_bf16 v[106:109], v[168:171], v[182:185], v[106:109]
	v_mfma_f32_16x16x32_bf16 v[102:105], v[156:159], v[190:193], v[102:105]
	v_mfma_f32_16x16x32_bf16 v[98:101], v[168:171], v[190:193], v[98:101]
	v_mfma_f32_16x16x32_bf16 v[82:85], v[156:159], v[198:201], v[82:85]
	v_mfma_f32_16x16x32_bf16 v[74:77], v[168:171], v[198:201], v[74:77]
	v_mfma_f32_16x16x32_bf16 v[70:73], v[156:159], v[206:209], v[70:73]
	v_mfma_f32_16x16x32_bf16 v[66:69], v[168:171], v[206:209], v[66:69]
	v_mfma_f32_16x16x32_bf16 v[118:121], v[164:167], v[186:189], v[118:121]
	v_mfma_f32_16x16x32_bf16 v[106:109], v[178:181], v[186:189], v[106:109]
	v_mfma_f32_16x16x32_bf16 v[102:105], v[164:167], v[194:197], v[102:105]
	v_mfma_f32_16x16x32_bf16 v[98:101], v[178:181], v[194:197], v[98:101]
	v_mfma_f32_16x16x32_bf16 v[82:85], v[164:167], v[202:205], v[82:85]
	v_mfma_f32_16x16x32_bf16 v[74:77], v[178:181], v[202:205], v[74:77]
	v_mfma_f32_16x16x32_bf16 v[70:73], v[164:167], v[210:213], v[70:73]
	v_mfma_f32_16x16x32_bf16 v[66:69], v[178:181], v[210:213], v[66:69]
	s_setprio 0
	s_barrier
	s_add_i32 s48, s48, s18
	v_lshl_add_u64 v[160:161], s[14:15], 0, v[0:1]
	s_mov_b32 m0, s48
	ds_read_b128 v[182:185], v163 offset:16384
	ds_read_b128 v[186:189], v163 offset:17408
	ds_read_b128 v[190:193], v163 offset:18432
	ds_read_b128 v[194:197], v163 offset:19456
	ds_read_b128 v[198:201], v163 offset:20480
	ds_read_b128 v[202:205], v163 offset:21504
	ds_read_b128 v[206:209], v163 offset:22528
	ds_read_b128 v[210:213], v163 offset:23552
	global_load_lds_dwordx4 v[160:161], off
	s_add_i32 m0, s48, 0x2000
	s_add_u32 s48, s14, 0x100000
	v_lshl_add_u64 v[214:215], s[14:15], 0, v[146:147]
	s_addc_u32 s49, s15, 0
	s_add_i32 s50, s50, s18
	global_load_lds_dwordx4 v[214:215], off
	v_lshl_add_u64 v[216:217], s[48:49], 0, v[0:1]
	s_mov_b32 m0, s50
	v_lshl_add_u64 v[218:219], s[16:17], 0, v[148:149]
	global_load_lds_dwordx4 v[216:217], off
	v_lshl_add_u64 v[216:217], s[48:49], 0, v[146:147]
	s_add_i32 m0, s50, 0x2000
	s_nop 0
	global_load_lds_dwordx4 v[216:217], off
	v_lshl_add_u64 v[216:217], s[16:17], 0, v[150:151]
	s_mov_b32 m0, s19
	s_nop 0
	global_load_lds_dwordx4 v[216:217], off
	s_mov_b32 m0, s20
	s_nop 0
	global_load_lds_dwordx4 v[218:219], off
	s_waitcnt vmcnt(8)
	s_waitcnt lgkmcnt(0)
	s_barrier
; #define WAIT_V(n) asm volatile("s_waitcnt vmcnt(" #n ")" ::: "memory")
; #define WAIT_L(n) asm volatile("s_waitcnt lgkmcnt(" #n ")" ::: "memory")
; #define BAR __builtin_amdgcn_s_barrier()
; #define SCHED __builtin_amdgcn_sched_barrier(0)
;     ...
;       WAIT_V(8); WAIT_L(0); BAR; MMA(1, 0, At, B0); MMA(1, 1, At, B1); BAR; SCHED;
;       LDB(B0, 1, 0); LDB(B1, 1, 1); SCHED; LDA(At, 1, 0); STAGE(SAo(0, 1), a2 + hstep, voff);
;       WAIT_V(8); WAIT_L(0); BAR; MMA(0, 0, At, B0); MMA(0, 1, At, B1); BAR; SCHED;
	s_setprio 1
	s_waitcnt lgkmcnt(0)
	v_mfma_f32_16x16x32_bf16 v[62:65], v[130:133], v[182:185], v[62:65]
	v_mfma_f32_16x16x32_bf16 v[58:61], v[138:141], v[182:185], v[58:61]
	v_mfma_f32_16x16x32_bf16 v[54:57], v[130:133], v[190:193], v[54:57]
	v_mfma_f32_16x16x32_bf16 v[46:49], v[138:141], v[190:193], v[46:49]
	v_mfma_f32_16x16x32_bf16 v[34:37], v[130:133], v[198:201], v[34:37]
	v_mfma_f32_16x16x32_bf16 v[26:29], v[138:141], v[198:201], v[26:29]
	v_mfma_f32_16x16x32_bf16 v[22:25], v[130:133], v[206:209], v[22:25]
	v_mfma_f32_16x16x32_bf16 v[14:17], v[138:141], v[206:209], v[14:17]
	v_mfma_f32_16x16x32_bf16 v[62:65], v[134:137], v[186:189], v[62:65]
	v_mfma_f32_16x16x32_bf16 v[58:61], v[142:145], v[186:189], v[58:61]
	v_mfma_f32_16x16x32_bf16 v[54:57], v[134:137], v[194:197], v[54:57]
	v_mfma_f32_16x16x32_bf16 v[46:49], v[142:145], v[194:197], v[46:49]
	v_mfma_f32_16x16x32_bf16 v[34:37], v[134:137], v[202:205], v[34:37]
	v_mfma_f32_16x16x32_bf16 v[26:29], v[142:145], v[202:205], v[26:29]
	v_mfma_f32_16x16x32_bf16 v[22:25], v[134:137], v[210:213], v[22:25]
	v_mfma_f32_16x16x32_bf16 v[14:17], v[142:145], v[210:213], v[14:17]
	s_setprio 0
	s_setprio 1
	v_mfma_f32_16x16x32_bf16 v[50:53], v[156:159], v[182:185], v[50:53]
	v_mfma_f32_16x16x32_bf16 v[42:45], v[168:171], v[182:185], v[42:45]
	v_mfma_f32_16x16x32_bf16 v[38:41], v[156:159], v[190:193], v[38:41]
	v_mfma_f32_16x16x32_bf16 v[30:33], v[168:171], v[190:193], v[30:33]
	v_mfma_f32_16x16x32_bf16 v[18:21], v[156:159], v[198:201], v[18:21]
	v_mfma_f32_16x16x32_bf16 v[10:13], v[168:171], v[198:201], v[10:13]
	v_mfma_f32_16x16x32_bf16 v[6:9], v[156:159], v[206:209], v[6:9]
	v_mfma_f32_16x16x32_bf16 v[2:5], v[168:171], v[206:209], v[2:5]
	v_mfma_f32_16x16x32_bf16 v[50:53], v[164:167], v[186:189], v[50:53]
	v_mfma_f32_16x16x32_bf16 v[42:45], v[178:181], v[186:189], v[42:45]
	v_mfma_f32_16x16x32_bf16 v[38:41], v[164:167], v[194:197], v[38:41]
	v_mfma_f32_16x16x32_bf16 v[30:33], v[178:181], v[194:197], v[30:33]
	v_mfma_f32_16x16x32_bf16 v[18:21], v[164:167], v[202:205], v[18:21]
	v_mfma_f32_16x16x32_bf16 v[10:13], v[178:181], v[202:205], v[10:13]
	v_mfma_f32_16x16x32_bf16 v[6:9], v[164:167], v[210:213], v[6:9]
	v_mfma_f32_16x16x32_bf16 v[2:5], v[178:181], v[210:213], v[2:5]
	s_setprio 0
	s_barrier
	s_add_i32 s48, 0, 0x18000
	s_add_i32 s49, 0, 0x1c000
	v_add_u32_e32 v142, s48, v162
	v_add_u32_e32 v178, s49, v162
	ds_read_b128 v[130:133], v142
	ds_read_b128 v[134:137], v142 offset:1024
	ds_read_b128 v[138:141], v142 offset:2048
	ds_read_b128 v[142:145], v142 offset:3072
	ds_read_b128 v[156:159], v178
	ds_read_b128 v[164:167], v178 offset:1024
	ds_read_b128 v[168:171], v178 offset:2048
	ds_read_b128 v[178:181], v178 offset:3072
	s_add_u32 s16, s16, 0x100000
	s_addc_u32 s17, s17, 0
	s_mov_b32 m0, s21
	v_lshl_add_u64 v[220:221], s[16:17], 0, v[150:151]
	ds_read_b128 v[182:185], v163 offset:32768
	ds_read_b128 v[186:189], v163 offset:33792
	ds_read_b128 v[190:193], v163 offset:34816
	ds_read_b128 v[194:197], v163 offset:35840
	ds_read_b128 v[198:201], v163 offset:36864
	ds_read_b128 v[202:205], v163 offset:37888
	ds_read_b128 v[206:209], v163 offset:38912
	ds_read_b128 v[210:213], v163 offset:39936
	global_load_lds_dwordx4 v[220:221], off
	v_lshl_add_u64 v[220:221], s[16:17], 0, v[148:149]
	s_mov_b32 m0, s22
	s_nop 0
	global_load_lds_dwordx4 v[220:221], off
	s_waitcnt vmcnt(8)
	s_waitcnt lgkmcnt(0)
	s_barrier
	s_setprio 1
	s_waitcnt lgkmcnt(0)
	v_mfma_f32_16x16x32_bf16 v[126:129], v[130:133], v[182:185], v[126:129]
	v_mfma_f32_16x16x32_bf16 v[122:125], v[138:141], v[182:185], v[122:125]
	v_mfma_f32_16x16x32_bf16 v[114:117], v[130:133], v[190:193], v[114:117]
	v_mfma_f32_16x16x32_bf16 v[110:113], v[138:141], v[190:193], v[110:113]
	v_mfma_f32_16x16x32_bf16 v[94:97], v[130:133], v[198:201], v[94:97]
	v_mfma_f32_16x16x32_bf16 v[90:93], v[138:141], v[198:201], v[90:93]
	v_mfma_f32_16x16x32_bf16 v[86:89], v[130:133], v[206:209], v[86:89]
	v_mfma_f32_16x16x32_bf16 v[78:81], v[138:141], v[206:209], v[78:81]
	v_mfma_f32_16x16x32_bf16 v[126:129], v[134:137], v[186:189], v[126:129]
	v_mfma_f32_16x16x32_bf16 v[122:125], v[142:145], v[186:189], v[122:125]
	v_mfma_f32_16x16x32_bf16 v[114:117], v[134:137], v[194:197], v[114:117]
	v_mfma_f32_16x16x32_bf16 v[110:113], v[142:145], v[194:197], v[110:113]
	v_mfma_f32_16x16x32_bf16 v[94:97], v[134:137], v[202:205], v[94:97]
	v_mfma_f32_16x16x32_bf16 v[90:93], v[142:145], v[202:205], v[90:93]
	v_mfma_f32_16x16x32_bf16 v[86:89], v[134:137], v[210:213], v[86:89]
	v_mfma_f32_16x16x32_bf16 v[78:81], v[142:145], v[210:213], v[78:81]
	s_setprio 0
	s_setprio 1
	v_mfma_f32_16x16x32_bf16 v[118:121], v[156:159], v[182:185], v[118:121]
	v_mfma_f32_16x16x32_bf16 v[106:109], v[168:171], v[182:185], v[106:109]
	v_mfma_f32_16x16x32_bf16 v[102:105], v[156:159], v[190:193], v[102:105]
	v_mfma_f32_16x16x32_bf16 v[98:101], v[168:171], v[190:193], v[98:101]
	v_mfma_f32_16x16x32_bf16 v[82:85], v[156:159], v[198:201], v[82:85]
	v_mfma_f32_16x16x32_bf16 v[74:77], v[168:171], v[198:201], v[74:77]
	v_mfma_f32_16x16x32_bf16 v[70:73], v[156:159], v[206:209], v[70:73]
	v_mfma_f32_16x16x32_bf16 v[66:69], v[168:171], v[206:209], v[66:69]
	v_mfma_f32_16x16x32_bf16 v[118:121], v[164:167], v[186:189], v[118:121]
	v_mfma_f32_16x16x32_bf16 v[106:109], v[178:181], v[186:189], v[106:109]
	v_mfma_f32_16x16x32_bf16 v[102:105], v[164:167], v[194:197], v[102:105]
	v_mfma_f32_16x16x32_bf16 v[98:101], v[178:181], v[194:197], v[98:101]
	v_mfma_f32_16x16x32_bf16 v[82:85], v[164:167], v[202:205], v[82:85]
	v_mfma_f32_16x16x32_bf16 v[74:77], v[178:181], v[202:205], v[74:77]
	v_mfma_f32_16x16x32_bf16 v[70:73], v[164:167], v[210:213], v[70:73]
	v_mfma_f32_16x16x32_bf16 v[66:69], v[178:181], v[210:213], v[66:69]
	s_setprio 0
	s_barrier
; #define WAIT_V(n) asm volatile("s_waitcnt vmcnt(" #n ")" ::: "memory")
; #define WAIT_L(n) asm volatile("s_waitcnt lgkmcnt(" #n ")" ::: "memory")
; #define BAR __builtin_amdgcn_s_barrier()
; #define SCHED __builtin_amdgcn_sched_barrier(0)
;     ...
;       LDA(At, 1, 1); STAGE(SBo(1, 0), b3, voffB); STAGE(SBo(1, 1), b3 + hstep, voffB); STAGE(SAo(1, 0), a3, voff);
;       WAIT_V(8); WAIT_L(0); BAR; MMA(1, 0, At, B0); MMA(1, 1, At, B1); BAR; SCHED;
;     }
	s_add_i32 s16, s48, s18
	v_lshl_add_u64 v[160:161], v[160:161], 0, s[34:35]
	s_mov_b32 m0, s16
	ds_read_b128 v[182:185], v163 offset:49152
	ds_read_b128 v[186:189], v163 offset:50176
	ds_read_b128 v[190:193], v163 offset:51200
	ds_read_b128 v[194:197], v163 offset:52224
	ds_read_b128 v[198:201], v163 offset:53248
	ds_read_b128 v[202:205], v163 offset:54272
	ds_read_b128 v[206:209], v163 offset:55296
	ds_read_b128 v[210:213], v163 offset:56320
	global_load_lds_dwordx4 v[160:161], off
	s_add_i32 m0, s16, 0x2000
	s_add_u32 s14, s14, 0x100080
	v_lshl_add_u64 v[160:161], v[214:215], 0, s[34:35]
	s_addc_u32 s15, s15, 0
	s_add_i32 s16, s49, s18
	global_load_lds_dwordx4 v[160:161], off
	v_lshl_add_u64 v[160:161], s[14:15], 0, v[0:1]
	s_mov_b32 m0, s16
	s_nop 0
	global_load_lds_dwordx4 v[160:161], off
	v_lshl_add_u64 v[160:161], s[14:15], 0, v[146:147]
	s_add_i32 m0, s16, 0x2000
	s_nop 0
	global_load_lds_dwordx4 v[160:161], off
	v_lshl_add_u64 v[160:161], v[216:217], 0, s[34:35]
	s_mov_b32 m0, s27
	s_nop 0
	global_load_lds_dwordx4 v[160:161], off
	v_lshl_add_u64 v[160:161], v[218:219], 0, s[34:35]
	s_mov_b32 m0, s29
	s_nop 0
	global_load_lds_dwordx4 v[160:161], off
	s_waitcnt vmcnt(8)
	s_waitcnt lgkmcnt(0)
	s_barrier
	s_setprio 1
	s_waitcnt lgkmcnt(0)
	v_mfma_f32_16x16x32_bf16 v[62:65], v[130:133], v[182:185], v[62:65]
	v_mfma_f32_16x16x32_bf16 v[58:61], v[138:141], v[182:185], v[58:61]
	v_mfma_f32_16x16x32_bf16 v[54:57], v[130:133], v[190:193], v[54:57]
	v_mfma_f32_16x16x32_bf16 v[46:49], v[138:141], v[190:193], v[46:49]
	v_mfma_f32_16x16x32_bf16 v[34:37], v[130:133], v[198:201], v[34:37]
	v_mfma_f32_16x16x32_bf16 v[26:29], v[138:141], v[198:201], v[26:29]
	v_mfma_f32_16x16x32_bf16 v[22:25], v[130:133], v[206:209], v[22:25]
	v_mfma_f32_16x16x32_bf16 v[14:17], v[138:141], v[206:209], v[14:17]
	v_mfma_f32_16x16x32_bf16 v[62:65], v[134:137], v[186:189], v[62:65]
	v_mfma_f32_16x16x32_bf16 v[58:61], v[142:145], v[186:189], v[58:61]
	v_mfma_f32_16x16x32_bf16 v[54:57], v[134:137], v[194:197], v[54:57]
	v_mfma_f32_16x16x32_bf16 v[46:49], v[142:145], v[194:197], v[46:49]
	v_mfma_f32_16x16x32_bf16 v[34:37], v[134:137], v[202:205], v[34:37]
	v_mfma_f32_16x16x32_bf16 v[26:29], v[142:145], v[202:205], v[26:29]
	v_mfma_f32_16x16x32_bf16 v[22:25], v[134:137], v[210:213], v[22:25]
	v_mfma_f32_16x16x32_bf16 v[14:17], v[142:145], v[210:213], v[14:17]
	s_setprio 0
	s_setprio 1
	v_mfma_f32_16x16x32_bf16 v[50:53], v[156:159], v[182:185], v[50:53]
	v_mfma_f32_16x16x32_bf16 v[42:45], v[168:171], v[182:185], v[42:45]
	v_mfma_f32_16x16x32_bf16 v[38:41], v[156:159], v[190:193], v[38:41]
	v_mfma_f32_16x16x32_bf16 v[30:33], v[168:171], v[190:193], v[30:33]
	v_mfma_f32_16x16x32_bf16 v[18:21], v[156:159], v[198:201], v[18:21]
	v_mfma_f32_16x16x32_bf16 v[10:13], v[168:171], v[198:201], v[10:13]
	v_mfma_f32_16x16x32_bf16 v[6:9], v[156:159], v[206:209], v[6:9]
	v_mfma_f32_16x16x32_bf16 v[2:5], v[168:171], v[206:209], v[2:5]
	v_mfma_f32_16x16x32_bf16 v[50:53], v[164:167], v[186:189], v[50:53]
	v_mfma_f32_16x16x32_bf16 v[42:45], v[178:181], v[186:189], v[42:45]
	v_mfma_f32_16x16x32_bf16 v[38:41], v[164:167], v[194:197], v[38:41]
	v_mfma_f32_16x16x32_bf16 v[30:33], v[178:181], v[194:197], v[30:33]
	v_mfma_f32_16x16x32_bf16 v[18:21], v[164:167], v[202:205], v[18:21]
	v_mfma_f32_16x16x32_bf16 v[10:13], v[178:181], v[202:205], v[10:13]
	v_mfma_f32_16x16x32_bf16 v[6:9], v[164:167], v[210:213], v[6:9]
	v_mfma_f32_16x16x32_bf16 v[2:5], v[178:181], v[210:213], v[2:5]
	s_setprio 0
	s_add_i32 s47, s47, 2
	s_add_u32 s12, s12, 0x100
	s_addc_u32 s13, s13, 0
	s_add_u32 s45, s45, 0x100
	s_addc_u32 s46, s46, 0
	s_cmp_gt_u32 s47, 61
	s_cbranch_scc1 .Lbe_m2_exit
	s_add_u32 s14, s12, 0xfff00080
	s_addc_u32 s15, s13, -1
	s_add_i32 s48, 0, 0x10000
	s_cmp_eq_u32 s47, 60
	s_cselect_b32 s17, s7, s15
	s_cselect_b32 s16, s42, s14
	s_cselect_b32 s15, s43, s46
	s_cselect_b32 s14, s44, s45
	s_add_i32 s50, 0, 0x14000
	s_branch .LBB0_1064

;     ...
;     const bool has_next = unit(ui + 1, npm, npn, nkq);
;     const char* nA = has_next ? (const char*)A + (size_t)npm * tstep + (nkq > 0 ? (size_t)nkq * (K / 4) * 2 : 0) : cA;
;     const char* nB = has_next ? (const char*)Bt + (size_t)npn * tstep + (nkq > 0 ? (size_t)nkq * (K / 4) * 2 : 0) : cB;
;     const int ntu = (SPLIT && kq >= 0) ? nt / 4 : nt;
;     for (int t = 0; t < ntu; t += 2) {
;       const bool last = (t == ntu - 2);
;       const char* a1 = cA + (size_t)(t + 1) * kstep;
;       const char* a2 = last ? nA : cA + (size_t)(t + 2) * kstep;
;       const char* b2 = last ? nB : cB + (size_t)(t + 2) * kstep;
;     ...
;     for (int a = 0; a < 2; ++a)
; #pragma unroll
;       for (int b = 0; b < 2; ++b)
; #pragma unroll
;         for (int m = 0; m < 4; ++m)
; #pragma unroll
;           for (int n = 0; n < 2; ++n) acc[a][b][m][n] = (f32x4){0.f, 0.f, 0.f, 0.f};
;     pm = npm; pn = npn; kq = nkq; cA = nA; cB = nB; ++ui;
.LBB0_1139:
	s_nop 0
	v_readlane_b32 s10, v254, 34
	v_readlane_b32 s11, v254, 35
	s_lshl_b64 s[10:11], s[10:11], 21
	s_add_u32 s10, s84, s10
	s_addc_u32 s11, s85, s11
	s_and_b64 s[12:13], s[0:1], exec
	s_cselect_b32 s15, s11, s19
	s_cselect_b32 s17, s10, s18
	s_lshl_b32 s12, s45, 21
	s_add_u32 s12, s24, s12
	s_addc_u32 s13, s25, 0
	s_and_b64 s[22:23], s[0:1], exec
	s_cselect_b32 s36, s13, s21
	s_cselect_b32 s37, s12, s20
	s_add_u32 s18, s18, 0x100080
	s_addc_u32 s19, s19, 0
	s_add_u32 s46, s20, 0x100
	v_mov_b32_e32 v2, 0
	s_addc_u32 s47, s21, 0
	s_mov_b32 s48, -2
	v_mov_b32_e32 v3, v2
	v_mov_b32_e32 v4, v2
	v_mov_b32_e32 v5, v2
	v_mov_b32_e32 v6, v2
	v_mov_b32_e32 v7, v2
	v_mov_b32_e32 v8, v2
	v_mov_b32_e32 v9, v2
	v_mov_b32_e32 v18, v2
	v_mov_b32_e32 v19, v2
	v_mov_b32_e32 v20, v2
	v_mov_b32_e32 v21, v2
	v_mov_b32_e32 v22, v2
	v_mov_b32_e32 v23, v2
	v_mov_b32_e32 v24, v2
	v_mov_b32_e32 v25, v2
	v_mov_b32_e32 v34, v2
	v_mov_b32_e32 v35, v2
	v_mov_b32_e32 v36, v2
	v_mov_b32_e32 v37, v2
	v_mov_b32_e32 v38, v2
	v_mov_b32_e32 v39, v2
	v_mov_b32_e32 v40, v2
	v_mov_b32_e32 v41, v2
	v_mov_b32_e32 v50, v2
	v_mov_b32_e32 v51, v2
	v_mov_b32_e32 v52, v2
	v_mov_b32_e32 v53, v2
	v_mov_b32_e32 v54, v2
	v_mov_b32_e32 v55, v2
	v_mov_b32_e32 v56, v2
	v_mov_b32_e32 v57, v2
	v_mov_b32_e32 v10, v2
	v_mov_b32_e32 v11, v2
	v_mov_b32_e32 v12, v2
	v_mov_b32_e32 v13, v2
	v_mov_b32_e32 v14, v2
	v_mov_b32_e32 v15, v2
	v_mov_b32_e32 v16, v2
	v_mov_b32_e32 v17, v2
	v_mov_b32_e32 v26, v2
	v_mov_b32_e32 v27, v2
	v_mov_b32_e32 v28, v2
	v_mov_b32_e32 v29, v2
	v_mov_b32_e32 v30, v2
	v_mov_b32_e32 v31, v2
	v_mov_b32_e32 v32, v2
	v_mov_b32_e32 v33, v2
	v_mov_b32_e32 v42, v2
	v_mov_b32_e32 v43, v2
	v_mov_b32_e32 v44, v2
	v_mov_b32_e32 v45, v2
	v_mov_b32_e32 v46, v2
	v_mov_b32_e32 v47, v2
	v_mov_b32_e32 v48, v2
	v_mov_b32_e32 v49, v2
	v_mov_b32_e32 v58, v2
	v_mov_b32_e32 v59, v2
	v_mov_b32_e32 v60, v2
	v_mov_b32_e32 v61, v2
	v_mov_b32_e32 v62, v2
	v_mov_b32_e32 v63, v2
	v_mov_b32_e32 v64, v2
	v_mov_b32_e32 v65, v2
	v_mov_b32_e32 v66, v2
	v_mov_b32_e32 v67, v2
	v_mov_b32_e32 v68, v2
	v_mov_b32_e32 v69, v2
	v_mov_b32_e32 v70, v2
	v_mov_b32_e32 v71, v2
	v_mov_b32_e32 v72, v2
	v_mov_b32_e32 v73, v2
	v_mov_b32_e32 v82, v2
	v_mov_b32_e32 v83, v2
	v_mov_b32_e32 v84, v2
	v_mov_b32_e32 v85, v2
	v_mov_b32_e32 v86, v2
	v_mov_b32_e32 v87, v2
	v_mov_b32_e32 v88, v2
	v_mov_b32_e32 v89, v2
	s_waitcnt vmcnt(0)
	v_mov_b32_e32 v98, v2
	v_mov_b32_e32 v99, v2
	v_mov_b32_e32 v100, v2
	v_mov_b32_e32 v101, v2
	v_mov_b32_e32 v102, v2
	v_mov_b32_e32 v103, v2
	v_mov_b32_e32 v104, v2
	v_mov_b32_e32 v105, v2
	v_mov_b32_e32 v114, v2
	v_mov_b32_e32 v115, v2
	v_mov_b32_e32 v116, v2
	v_mov_b32_e32 v117, v2
	v_mov_b32_e32 v118, v2
	v_mov_b32_e32 v119, v2
	v_mov_b32_e32 v120, v2
	v_mov_b32_e32 v121, v2
	v_mov_b32_e32 v74, v2
	v_mov_b32_e32 v75, v2
	v_mov_b32_e32 v76, v2
	v_mov_b32_e32 v77, v2
	v_mov_b32_e32 v78, v2
	v_mov_b32_e32 v79, v2
	v_mov_b32_e32 v80, v2
	v_mov_b32_e32 v81, v2
	v_mov_b32_e32 v90, v2
	v_mov_b32_e32 v91, v2
	v_mov_b32_e32 v92, v2
	v_mov_b32_e32 v93, v2
	v_mov_b32_e32 v94, v2
	v_mov_b32_e32 v95, v2
	v_mov_b32_e32 v96, v2
	v_mov_b32_e32 v97, v2
	v_mov_b32_e32 v106, v2
	v_mov_b32_e32 v107, v2
	v_mov_b32_e32 v108, v2
	v_mov_b32_e32 v109, v2
	v_mov_b32_e32 v110, v2
	v_mov_b32_e32 v111, v2
	v_mov_b32_e32 v112, v2
	v_mov_b32_e32 v113, v2
	v_mov_b32_e32 v122, v2
	v_mov_b32_e32 v123, v2
	v_mov_b32_e32 v124, v2
	v_mov_b32_e32 v125, v2
	v_mov_b32_e32 v126, v2
	v_mov_b32_e32 v127, v2
	v_mov_b32_e32 v128, v2
	v_mov_b32_e32 v129, v2
	s_add_u32 s20, s18, 0xfff00080
	s_addc_u32 s21, s19, -1
	s_add_i32 s49, 0, 0x10000
	s_cmp_eq_u32 s48, 60
	s_cselect_b32 s23, s15, s21
	s_cselect_b32 s22, s17, s20
	s_cselect_b32 s21, s36, s47
	s_cselect_b32 s20, s37, s46
	s_add_i32 s52, 0, 0x14000
	s_branch .Lbe_mf_body

; #define WAIT_V(n) asm volatile("s_waitcnt vmcnt(" #n ")" ::: "memory")
; #define WAIT_L(n) asm volatile("s_waitcnt lgkmcnt(" #n ")" ::: "memory")
; #define BAR __builtin_amdgcn_s_barrier()
; #define SCHED __builtin_amdgcn_sched_barrier(0)
;     ...
;       LDB(B0, 0, 0); LDB(B1, 0, 1); SCHED; LDA(At, 0, 0); STAGE(SAo(1, 1), a1 + hstep, voff);
;       WAIT_V(8); WAIT_L(0); BAR; MMA(0, 0, At, B0); MMA(0, 1, At, B1); BAR; SCHED;
;       LDA(At, 0, 1); STAGE(SBo(0, 0), b2, voffB); STAGE(SBo(0, 1), b2 + hstep, voffB); STAGE(SAo(0, 0), a2, voff);
;       WAIT_V(8); WAIT_L(0); BAR; MMA(1, 0, At, B0); MMA(1, 1, At, B1); BAR; SCHED;
.Lbe_mf_body:
	v_add_u32_e32 v142, s49, v184
	v_add_u32_e32 v158, s52, v184
	ds_read_b128 v[130:133], v142
	ds_read_b128 v[134:137], v142 offset:1024
	ds_read_b128 v[138:141], v142 offset:2048
	ds_read_b128 v[142:145], v142 offset:3072
	ds_read_b128 v[146:149], v158
	ds_read_b128 v[150:153], v158 offset:1024
	ds_read_b128 v[154:157], v158 offset:2048
	ds_read_b128 v[158:161], v158 offset:3072
	v_lshl_add_u64 v[182:183], s[18:19], 0, v[168:169]
	s_add_i32 m0, s27, 0xc000
	ds_read_b128 v[178:181], v185
	ds_read_b128 v[186:189], v185 offset:1024
	ds_read_b128 v[190:193], v185 offset:2048
	ds_read_b128 v[194:197], v185 offset:3072
	ds_read_b128 v[198:201], v185 offset:4096
	ds_read_b128 v[202:205], v185 offset:5120
	ds_read_b128 v[206:209], v185 offset:6144
	ds_read_b128 v[210:213], v185 offset:7168
	global_load_lds_dwordx4 v[182:183], off
	v_lshl_add_u64 v[182:183], s[18:19], 0, v[170:171]
	s_add_i32 m0, s27, 0xe000
	s_nop 0
	global_load_lds_dwordx4 v[182:183], off
	s_waitcnt vmcnt(8)
	s_waitcnt lgkmcnt(0)
	s_barrier
	s_setprio 1
	s_waitcnt lgkmcnt(0)
	v_mfma_f32_16x16x32_bf16 v[126:129], v[130:133], v[178:181], v[126:129]
	v_mfma_f32_16x16x32_bf16 v[122:125], v[138:141], v[178:181], v[122:125]
	v_mfma_f32_16x16x32_bf16 v[110:113], v[130:133], v[190:193], v[110:113]
	v_mfma_f32_16x16x32_bf16 v[106:109], v[138:141], v[190:193], v[106:109]
	v_mfma_f32_16x16x32_bf16 v[94:97], v[130:133], v[198:201], v[94:97]
	v_mfma_f32_16x16x32_bf16 v[90:93], v[138:141], v[198:201], v[90:93]
	v_mfma_f32_16x16x32_bf16 v[78:81], v[130:133], v[206:209], v[78:81]
	v_mfma_f32_16x16x32_bf16 v[74:77], v[138:141], v[206:209], v[74:77]
	v_mfma_f32_16x16x32_bf16 v[126:129], v[134:137], v[186:189], v[126:129]
	v_mfma_f32_16x16x32_bf16 v[122:125], v[142:145], v[186:189], v[122:125]
	v_mfma_f32_16x16x32_bf16 v[110:113], v[134:137], v[194:197], v[110:113]
	v_mfma_f32_16x16x32_bf16 v[106:109], v[142:145], v[194:197], v[106:109]
	v_mfma_f32_16x16x32_bf16 v[94:97], v[134:137], v[202:205], v[94:97]
	v_mfma_f32_16x16x32_bf16 v[90:93], v[142:145], v[202:205], v[90:93]
	v_mfma_f32_16x16x32_bf16 v[78:81], v[134:137], v[210:213], v[78:81]
	v_mfma_f32_16x16x32_bf16 v[74:77], v[142:145], v[210:213], v[74:77]
	s_setprio 0
	s_setprio 1
	v_mfma_f32_16x16x32_bf16 v[118:121], v[146:149], v[178:181], v[118:121]
	v_mfma_f32_16x16x32_bf16 v[114:117], v[154:157], v[178:181], v[114:117]
	v_mfma_f32_16x16x32_bf16 v[102:105], v[146:149], v[190:193], v[102:105]
	v_mfma_f32_16x16x32_bf16 v[98:101], v[154:157], v[190:193], v[98:101]
	v_mfma_f32_16x16x32_bf16 v[86:89], v[146:149], v[198:201], v[86:89]
	v_mfma_f32_16x16x32_bf16 v[82:85], v[154:157], v[198:201], v[82:85]
	v_mfma_f32_16x16x32_bf16 v[70:73], v[146:149], v[206:209], v[70:73]
	v_mfma_f32_16x16x32_bf16 v[66:69], v[154:157], v[206:209], v[66:69]
	v_mfma_f32_16x16x32_bf16 v[118:121], v[150:153], v[186:189], v[118:121]
	v_mfma_f32_16x16x32_bf16 v[114:117], v[158:161], v[186:189], v[114:117]
	v_mfma_f32_16x16x32_bf16 v[102:105], v[150:153], v[194:197], v[102:105]
	v_mfma_f32_16x16x32_bf16 v[98:101], v[158:161], v[194:197], v[98:101]
	v_mfma_f32_16x16x32_bf16 v[86:89], v[150:153], v[202:205], v[86:89]
	v_mfma_f32_16x16x32_bf16 v[82:85], v[158:161], v[202:205], v[82:85]
	v_mfma_f32_16x16x32_bf16 v[70:73], v[150:153], v[210:213], v[70:73]
	v_mfma_f32_16x16x32_bf16 v[66:69], v[158:161], v[210:213], v[66:69]
	s_setprio 0
	s_barrier
	s_add_i32 s49, s49, s26
	v_lshl_add_u64 v[182:183], s[20:21], 0, v[0:1]
	s_mov_b32 m0, s49
	ds_read_b128 v[178:181], v185 offset:16384
	ds_read_b128 v[186:189], v185 offset:17408
	ds_read_b128 v[190:193], v185 offset:18432
	ds_read_b128 v[194:197], v185 offset:19456
	ds_read_b128 v[198:201], v185 offset:20480
	ds_read_b128 v[202:205], v185 offset:21504
	ds_read_b128 v[206:209], v185 offset:22528
	ds_read_b128 v[210:213], v185 offset:23552
	global_load_lds_dwordx4 v[182:183], off
	s_add_i32 m0, s49, 0x2000
	s_add_u32 s50, s20, 0x100000
	v_lshl_add_u64 v[214:215], s[20:21], 0, v[166:167]
	s_addc_u32 s51, s21, 0
	s_add_i32 s49, s52, s26
	global_load_lds_dwordx4 v[214:215], off
	v_lshl_add_u64 v[216:217], s[50:51], 0, v[0:1]
	s_mov_b32 m0, s49
	v_lshl_add_u64 v[218:219], s[22:23], 0, v[164:165]
	global_load_lds_dwordx4 v[216:217], off
	v_lshl_add_u64 v[216:217], s[50:51], 0, v[166:167]
	s_add_i32 m0, s49, 0x2000
	s_nop 0
	global_load_lds_dwordx4 v[216:217], off
	v_lshl_add_u64 v[216:217], s[22:23], 0, v[162:163]
	s_mov_b32 m0, s27
	s_nop 0
	global_load_lds_dwordx4 v[216:217], off
	s_mov_b32 m0, s29
	s_nop 0
	global_load_lds_dwordx4 v[218:219], off
	s_waitcnt vmcnt(8)
	s_waitcnt lgkmcnt(0)
	s_barrier
; #define WAIT_V(n) asm volatile("s_waitcnt vmcnt(" #n ")" ::: "memory")
; #define WAIT_L(n) asm volatile("s_waitcnt lgkmcnt(" #n ")" ::: "memory")
; #define BAR __builtin_amdgcn_s_barrier()
; #define SCHED __builtin_amdgcn_sched_barrier(0)
;     ...
;       WAIT_V(8); WAIT_L(0); BAR; MMA(1, 0, At, B0); MMA(1, 1, At, B1); BAR; SCHED;
;       LDB(B0, 1, 0); LDB(B1, 1, 1); SCHED; LDA(At, 1, 0); STAGE(SAo(0, 1), a2 + hstep, voff);
;       WAIT_V(8); WAIT_L(0); BAR; MMA(0, 0, At, B0); MMA(0, 1, At, B1); BAR; SCHED;
	s_setprio 1
	s_waitcnt lgkmcnt(0)
	v_mfma_f32_16x16x32_bf16 v[62:65], v[130:133], v[178:181], v[62:65]
	v_mfma_f32_16x16x32_bf16 v[58:61], v[138:141], v[178:181], v[58:61]
	v_mfma_f32_16x16x32_bf16 v[46:49], v[130:133], v[190:193], v[46:49]
	v_mfma_f32_16x16x32_bf16 v[42:45], v[138:141], v[190:193], v[42:45]
	v_mfma_f32_16x16x32_bf16 v[30:33], v[130:133], v[198:201], v[30:33]
	v_mfma_f32_16x16x32_bf16 v[26:29], v[138:141], v[198:201], v[26:29]
	v_mfma_f32_16x16x32_bf16 v[14:17], v[130:133], v[206:209], v[14:17]
	v_mfma_f32_16x16x32_bf16 v[10:13], v[138:141], v[206:209], v[10:13]
	v_mfma_f32_16x16x32_bf16 v[62:65], v[134:137], v[186:189], v[62:65]
	v_mfma_f32_16x16x32_bf16 v[58:61], v[142:145], v[186:189], v[58:61]
	v_mfma_f32_16x16x32_bf16 v[46:49], v[134:137], v[194:197], v[46:49]
	v_mfma_f32_16x16x32_bf16 v[42:45], v[142:145], v[194:197], v[42:45]
	v_mfma_f32_16x16x32_bf16 v[30:33], v[134:137], v[202:205], v[30:33]
	v_mfma_f32_16x16x32_bf16 v[26:29], v[142:145], v[202:205], v[26:29]
	v_mfma_f32_16x16x32_bf16 v[14:17], v[134:137], v[210:213], v[14:17]
	v_mfma_f32_16x16x32_bf16 v[10:13], v[142:145], v[210:213], v[10:13]
	s_setprio 0
	s_setprio 1
	v_mfma_f32_16x16x32_bf16 v[54:57], v[146:149], v[178:181], v[54:57]
	v_mfma_f32_16x16x32_bf16 v[50:53], v[154:157], v[178:181], v[50:53]
	v_mfma_f32_16x16x32_bf16 v[38:41], v[146:149], v[190:193], v[38:41]
	v_mfma_f32_16x16x32_bf16 v[34:37], v[154:157], v[190:193], v[34:37]
	v_mfma_f32_16x16x32_bf16 v[22:25], v[146:149], v[198:201], v[22:25]
	v_mfma_f32_16x16x32_bf16 v[18:21], v[154:157], v[198:201], v[18:21]
	v_mfma_f32_16x16x32_bf16 v[6:9], v[146:149], v[206:209], v[6:9]
	v_mfma_f32_16x16x32_bf16 v[2:5], v[154:157], v[206:209], v[2:5]
	v_mfma_f32_16x16x32_bf16 v[54:57], v[150:153], v[186:189], v[54:57]
	v_mfma_f32_16x16x32_bf16 v[50:53], v[158:161], v[186:189], v[50:53]
	v_mfma_f32_16x16x32_bf16 v[38:41], v[150:153], v[194:197], v[38:41]
	v_mfma_f32_16x16x32_bf16 v[34:37], v[158:161], v[194:197], v[34:37]
	v_mfma_f32_16x16x32_bf16 v[22:25], v[150:153], v[202:205], v[22:25]
	v_mfma_f32_16x16x32_bf16 v[18:21], v[158:161], v[202:205], v[18:21]
	v_mfma_f32_16x16x32_bf16 v[6:9], v[150:153], v[210:213], v[6:9]
	v_mfma_f32_16x16x32_bf16 v[2:5], v[158:161], v[210:213], v[2:5]
	s_setprio 0
	s_barrier
	s_add_i32 s49, 0, 0x18000
	s_add_i32 s50, 0, 0x1c000
	v_add_u32_e32 v142, s49, v184
	v_add_u32_e32 v158, s50, v184
	ds_read_b128 v[130:133], v142
	ds_read_b128 v[134:137], v142 offset:1024
	ds_read_b128 v[138:141], v142 offset:2048
	ds_read_b128 v[142:145], v142 offset:3072
	ds_read_b128 v[146:149], v158
	ds_read_b128 v[150:153], v158 offset:1024
	ds_read_b128 v[154:157], v158 offset:2048
	ds_read_b128 v[158:161], v158 offset:3072
	s_add_u32 s22, s22, 0x100000
	s_addc_u32 s23, s23, 0
	s_mov_b32 m0, s30
	v_lshl_add_u64 v[220:221], s[22:23], 0, v[162:163]
	ds_read_b128 v[178:181], v185 offset:32768
	ds_read_b128 v[186:189], v185 offset:33792
	ds_read_b128 v[190:193], v185 offset:34816
	ds_read_b128 v[194:197], v185 offset:35840
	ds_read_b128 v[198:201], v185 offset:36864
	ds_read_b128 v[202:205], v185 offset:37888
	ds_read_b128 v[206:209], v185 offset:38912
	ds_read_b128 v[210:213], v185 offset:39936
	global_load_lds_dwordx4 v[220:221], off
	v_lshl_add_u64 v[220:221], s[22:23], 0, v[164:165]
	s_mov_b32 m0, s31
	s_nop 0
	global_load_lds_dwordx4 v[220:221], off
	s_waitcnt vmcnt(8)
	s_waitcnt lgkmcnt(0)
	s_barrier
	s_setprio 1
	s_waitcnt lgkmcnt(0)
	v_mfma_f32_16x16x32_bf16 v[126:129], v[130:133], v[178:181], v[126:129]
	v_mfma_f32_16x16x32_bf16 v[122:125], v[138:141], v[178:181], v[122:125]
	v_mfma_f32_16x16x32_bf16 v[110:113], v[130:133], v[190:193], v[110:113]
	v_mfma_f32_16x16x32_bf16 v[106:109], v[138:141], v[190:193], v[106:109]
	v_mfma_f32_16x16x32_bf16 v[94:97], v[130:133], v[198:201], v[94:97]
	v_mfma_f32_16x16x32_bf16 v[90:93], v[138:141], v[198:201], v[90:93]
	v_mfma_f32_16x16x32_bf16 v[78:81], v[130:133], v[206:209], v[78:81]
	v_mfma_f32_16x16x32_bf16 v[74:77], v[138:141], v[206:209], v[74:77]
	v_mfma_f32_16x16x32_bf16 v[126:129], v[134:137], v[186:189], v[126:129]
	v_mfma_f32_16x16x32_bf16 v[122:125], v[142:145], v[186:189], v[122:125]
	v_mfma_f32_16x16x32_bf16 v[110:113], v[134:137], v[194:197], v[110:113]
	v_mfma_f32_16x16x32_bf16 v[106:109], v[142:145], v[194:197], v[106:109]
	v_mfma_f32_16x16x32_bf16 v[94:97], v[134:137], v[202:205], v[94:97]
	v_mfma_f32_16x16x32_bf16 v[90:93], v[142:145], v[202:205], v[90:93]
	v_mfma_f32_16x16x32_bf16 v[78:81], v[134:137], v[210:213], v[78:81]
	v_mfma_f32_16x16x32_bf16 v[74:77], v[142:145], v[210:213], v[74:77]
	s_setprio 0
	s_setprio 1
	v_mfma_f32_16x16x32_bf16 v[118:121], v[146:149], v[178:181], v[118:121]
	v_mfma_f32_16x16x32_bf16 v[114:117], v[154:157], v[178:181], v[114:117]
	v_mfma_f32_16x16x32_bf16 v[102:105], v[146:149], v[190:193], v[102:105]
	v_mfma_f32_16x16x32_bf16 v[98:101], v[154:157], v[190:193], v[98:101]
	v_mfma_f32_16x16x32_bf16 v[86:89], v[146:149], v[198:201], v[86:89]
	v_mfma_f32_16x16x32_bf16 v[82:85], v[154:157], v[198:201], v[82:85]
	v_mfma_f32_16x16x32_bf16 v[70:73], v[146:149], v[206:209], v[70:73]
	v_mfma_f32_16x16x32_bf16 v[66:69], v[154:157], v[206:209], v[66:69]
	v_mfma_f32_16x16x32_bf16 v[118:121], v[150:153], v[186:189], v[118:121]
	v_mfma_f32_16x16x32_bf16 v[114:117], v[158:161], v[186:189], v[114:117]
	v_mfma_f32_16x16x32_bf16 v[102:105], v[150:153], v[194:197], v[102:105]
	v_mfma_f32_16x16x32_bf16 v[98:101], v[158:161], v[194:197], v[98:101]
	v_mfma_f32_16x16x32_bf16 v[86:89], v[150:153], v[202:205], v[86:89]
	v_mfma_f32_16x16x32_bf16 v[82:85], v[158:161], v[202:205], v[82:85]
	v_mfma_f32_16x16x32_bf16 v[70:73], v[150:153], v[210:213], v[70:73]
	v_mfma_f32_16x16x32_bf16 v[66:69], v[158:161], v[210:213], v[66:69]
	s_setprio 0
	s_barrier
; #define WAIT_V(n) asm volatile("s_waitcnt vmcnt(" #n ")" ::: "memory")
; #define WAIT_L(n) asm volatile("s_waitcnt lgkmcnt(" #n ")" ::: "memory")
; #define BAR __builtin_amdgcn_s_barrier()
; #define SCHED __builtin_amdgcn_sched_barrier(0)
;     ...
;       LDA(At, 1, 1); STAGE(SBo(1, 0), b3, voffB); STAGE(SBo(1, 1), b3 + hstep, voffB); STAGE(SAo(1, 0), a3, voff);
;       WAIT_V(8); WAIT_L(0); BAR; MMA(1, 0, At, B0); MMA(1, 1, At, B1); BAR; SCHED;
;     }
	s_add_i32 s22, s49, s26
	v_lshl_add_u64 v[182:183], v[182:183], 0, s[34:35]
	s_mov_b32 m0, s22
	ds_read_b128 v[178:181], v185 offset:49152
	ds_read_b128 v[186:189], v185 offset:50176
	ds_read_b128 v[190:193], v185 offset:51200
	ds_read_b128 v[194:197], v185 offset:52224
	ds_read_b128 v[198:201], v185 offset:53248
	ds_read_b128 v[202:205], v185 offset:54272
	ds_read_b128 v[206:209], v185 offset:55296
	ds_read_b128 v[210:213], v185 offset:56320
	global_load_lds_dwordx4 v[182:183], off
	s_add_i32 m0, s22, 0x2000
	s_add_u32 s20, s20, 0x100080
	v_lshl_add_u64 v[182:183], v[214:215], 0, s[34:35]
	s_addc_u32 s21, s21, 0
	s_add_i32 s22, s50, s26
	global_load_lds_dwordx4 v[182:183], off
	v_lshl_add_u64 v[182:183], s[20:21], 0, v[0:1]
	s_mov_b32 m0, s22
	s_nop 0
	global_load_lds_dwordx4 v[182:183], off
	v_lshl_add_u64 v[182:183], s[20:21], 0, v[166:167]
	s_add_i32 m0, s22, 0x2000
	s_nop 0
	global_load_lds_dwordx4 v[182:183], off
	v_lshl_add_u64 v[182:183], v[216:217], 0, s[34:35]
	s_mov_b32 m0, s39
	s_nop 0
	global_load_lds_dwordx4 v[182:183], off
	v_lshl_add_u64 v[182:183], v[218:219], 0, s[34:35]
	s_mov_b32 m0, s42
	s_nop 0
	global_load_lds_dwordx4 v[182:183], off
	s_waitcnt vmcnt(8)
	s_waitcnt lgkmcnt(0)
	s_barrier
	s_setprio 1
	s_waitcnt lgkmcnt(0)
	v_mfma_f32_16x16x32_bf16 v[62:65], v[130:133], v[178:181], v[62:65]
	v_mfma_f32_16x16x32_bf16 v[58:61], v[138:141], v[178:181], v[58:61]
	v_mfma_f32_16x16x32_bf16 v[46:49], v[130:133], v[190:193], v[46:49]
	v_mfma_f32_16x16x32_bf16 v[42:45], v[138:141], v[190:193], v[42:45]
	v_mfma_f32_16x16x32_bf16 v[30:33], v[130:133], v[198:201], v[30:33]
	v_mfma_f32_16x16x32_bf16 v[26:29], v[138:141], v[198:201], v[26:29]
	v_mfma_f32_16x16x32_bf16 v[14:17], v[130:133], v[206:209], v[14:17]
	v_mfma_f32_16x16x32_bf16 v[10:13], v[138:141], v[206:209], v[10:13]
	v_mfma_f32_16x16x32_bf16 v[62:65], v[134:137], v[186:189], v[62:65]
	v_mfma_f32_16x16x32_bf16 v[58:61], v[142:145], v[186:189], v[58:61]
	v_mfma_f32_16x16x32_bf16 v[46:49], v[134:137], v[194:197], v[46:49]
	v_mfma_f32_16x16x32_bf16 v[42:45], v[142:145], v[194:197], v[42:45]
	v_mfma_f32_16x16x32_bf16 v[30:33], v[134:137], v[202:205], v[30:33]
	v_mfma_f32_16x16x32_bf16 v[26:29], v[142:145], v[202:205], v[26:29]
	v_mfma_f32_16x16x32_bf16 v[14:17], v[134:137], v[210:213], v[14:17]
	v_mfma_f32_16x16x32_bf16 v[10:13], v[142:145], v[210:213], v[10:13]
	s_setprio 0
	s_setprio 1
	v_mfma_f32_16x16x32_bf16 v[54:57], v[146:149], v[178:181], v[54:57]
	v_mfma_f32_16x16x32_bf16 v[50:53], v[154:157], v[178:181], v[50:53]
	v_mfma_f32_16x16x32_bf16 v[38:41], v[146:149], v[190:193], v[38:41]
	v_mfma_f32_16x16x32_bf16 v[34:37], v[154:157], v[190:193], v[34:37]
	v_mfma_f32_16x16x32_bf16 v[22:25], v[146:149], v[198:201], v[22:25]
	v_mfma_f32_16x16x32_bf16 v[18:21], v[154:157], v[198:201], v[18:21]
	v_mfma_f32_16x16x32_bf16 v[6:9], v[146:149], v[206:209], v[6:9]
	v_mfma_f32_16x16x32_bf16 v[2:5], v[154:157], v[206:209], v[2:5]
	v_mfma_f32_16x16x32_bf16 v[54:57], v[150:153], v[186:189], v[54:57]
	v_mfma_f32_16x16x32_bf16 v[50:53], v[158:161], v[186:189], v[50:53]
	v_mfma_f32_16x16x32_bf16 v[38:41], v[150:153], v[194:197], v[38:41]
	v_mfma_f32_16x16x32_bf16 v[34:37], v[158:161], v[194:197], v[34:37]
	v_mfma_f32_16x16x32_bf16 v[22:25], v[150:153], v[202:205], v[22:25]
	v_mfma_f32_16x16x32_bf16 v[18:21], v[158:161], v[202:205], v[18:21]
	v_mfma_f32_16x16x32_bf16 v[6:9], v[150:153], v[210:213], v[6:9]
	v_mfma_f32_16x16x32_bf16 v[2:5], v[158:161], v[210:213], v[2:5]
	s_setprio 0
	s_add_i32 s48, s48, 2
	s_add_u32 s18, s18, 0x100
	s_addc_u32 s19, s19, 0
	s_add_u32 s46, s46, 0x100
	s_addc_u32 s47, s47, 0
	s_cmp_gt_u32 s48, 61
	s_cbranch_scc1 .Lbe_mf_exit
	s_add_u32 s20, s18, 0xfff00080
	s_addc_u32 s21, s19, -1
	s_add_i32 s49, 0, 0x10000
	s_cmp_eq_u32 s48, 60
	s_cselect_b32 s23, s15, s21
	s_cselect_b32 s22, s17, s20
	s_cselect_b32 s21, s36, s47
	s_cselect_b32 s20, s37, s46
	s_add_i32 s52, 0, 0x14000
	s_branch .LBB0_1140
